# nt hints extended: streaming f32 weight loads (mod_task, transposes), h_in / conv raw / s5 B-tile staging loads
# baseline (speedup 1.0000x reference)
.LBB0_188:
	s_lshl_b32 s88, s17, 14
	s_nop 0
	v_lshl_add_u64 v[34:35], v[186:187], 0, s[88:89]
	v_lshl_add_u64 v[36:37], v[34:35], 0, v[64:65]
	v_lshl_add_u64 v[44:45], v[34:35], 0, v[84:85]
	v_lshl_add_u64 v[48:49], v[34:35], 0, v[78:79]
	v_lshl_add_u64 v[38:39], v[34:35], 0, v[82:83]
	global_load_dwordx4 v[34:37], v[36:37], off nt
	s_nop 0
	global_load_dwordx4 v[40:43], v[38:39], off nt
	s_nop 0
	global_load_dwordx4 v[44:47], v[44:45], off nt
	s_nop 0
	global_load_dwordx4 v[48:51], v[48:49], off nt
	s_lshl_b32 s16, s17, 9
	s_add_i32 s16, s16, 0x11800
	v_lshl_add_u32 v39, v62, 2, s16
	v_lshl_or_b32 v38, v219, 2, s16
	s_lshl_b32 s21, s17, 1
	s_sub_i32 s27, 1, s21
	s_mov_b32 s64, 0x5040100
	v_cndmask_b32_e64 v189, 3, v220, s[2:3]
	s_waitcnt vmcnt(3)
	ds_write_b128 v222, v[34:37]
	s_waitcnt vmcnt(2)
	ds_write_b128 v223, v[40:43]
	s_waitcnt vmcnt(1)
	ds_write_b128 v224, v[44:47]
	s_waitcnt vmcnt(0)
	ds_write_b128 v225, v[48:51]
	ds_read_b128 v[34:37], v39
	ds_read_b32 v40, v38
	v_mul_lo_u32 v44, s27, v226
	v_mul_lo_u32 v46, s27, v1
	v_cmp_gt_i32_e64 s[4:5], 1, v44
	v_cmp_gt_i32_e64 s[8:9], s21, v44
	s_waitcnt lgkmcnt(0)
	v_sub_f32_e32 v41, v40, v34
	v_sub_f32_e32 v42, v40, v35
	v_sub_f32_e32 v43, v40, v36
	v_sub_f32_e32 v40, v40, v37
	v_mul_f32_e32 v41, 0x3fb8aa3b, v41
	v_mul_f32_e32 v42, 0x3fb8aa3b, v42
	v_mul_f32_e32 v43, 0x3fb8aa3b, v43
	v_mul_f32_e32 v45, 0x3fb8aa3b, v40
	v_exp_f32_e32 v40, v41
	v_exp_f32_e32 v41, v42
	v_exp_f32_e32 v42, v43
	v_exp_f32_e32 v43, v45
	v_mul_lo_u32 v45, s27, v74
	v_pk_mul_f32 v[40:41], v[40:41], v[70:71]
	v_cmp_gt_i32_e32 vcc, 1, v45
	v_pk_mul_f32 v[42:43], v[42:43], v[72:73]
	v_cvt_pk_bf16_f32 v40, v40, v41
	v_cvt_pk_bf16_f32 v41, v42, v43
	v_cndmask_b32_e64 v42, 0, v40, s[4:5]
	v_lshrrev_b32_e32 v40, 16, v40
	v_cndmask_b32_e32 v43, 0, v41, vcc
	v_lshrrev_b32_e32 v41, 16, v41
	v_cmp_gt_i32_e64 s[6:7], 1, v46
	v_cndmask_b32_e64 v40, 0, v40, s[8:9]
	v_perm_b32 v40, v40, v42, s64
	v_cndmask_b32_e64 v41, 0, v41, s[6:7]
	v_perm_b32 v41, v41, v43, s64
	ds_write_b64 v155, v[40:41]
	ds_read_b32 v40, v38 offset:64
	v_mul_lo_u32 v44, s27, v227
	v_cmp_gt_i32_e64 s[0:1], 1, v44
	v_mul_lo_u32 v46, s27, v63
	s_waitcnt lgkmcnt(0)
	v_sub_f32_e32 v41, v40, v34
	v_sub_f32_e32 v42, v40, v35
	v_sub_f32_e32 v43, v40, v36
	v_sub_f32_e32 v40, v40, v37
	v_mul_f32_e32 v41, 0x3fb8aa3b, v41
	v_mul_f32_e32 v42, 0x3fb8aa3b, v42
	v_mul_f32_e32 v43, 0x3fb8aa3b, v43
	v_mul_f32_e32 v45, 0x3fb8aa3b, v40
	v_exp_f32_e32 v40, v41
	v_exp_f32_e32 v41, v42
	v_exp_f32_e32 v42, v43
	v_exp_f32_e32 v43, v45
	v_mul_lo_u32 v45, s27, v86
	v_pk_mul_f32 v[40:41], v[40:41], v[76:77]
	v_pk_mul_f32 v[42:43], v[42:43], v[80:81]
	v_cvt_pk_bf16_f32 v40, v40, v41
	v_cvt_pk_bf16_f32 v41, v42, v43
	v_cndmask_b32_e64 v42, 0, v40, s[0:1]
	v_cmp_gt_i32_e64 s[0:1], 1, v45
	v_lshrrev_b32_e32 v40, 16, v40
	s_nop 0
	v_cndmask_b32_e64 v43, 0, v41, s[0:1]
	v_cmp_gt_i32_e64 s[0:1], s21, v44
	v_lshrrev_b32_e32 v41, 16, v41
	v_mul_lo_u32 v44, s27, v228
	v_cndmask_b32_e64 v40, 0, v40, s[0:1]
	v_cmp_gt_i32_e64 s[0:1], 1, v46
	v_perm_b32 v40, v40, v42, s64
	v_mul_lo_u32 v46, s27, v75
	v_cndmask_b32_e64 v41, 0, v41, s[0:1]
	v_perm_b32 v41, v41, v43, s64
	ds_write_b64 v155, v[40:41] offset:4352
	ds_read_b32 v40, v38 offset:128
	v_cmp_gt_i32_e64 s[0:1], 1, v44
	s_waitcnt lgkmcnt(0)
	v_sub_f32_e32 v41, v40, v34
	v_sub_f32_e32 v42, v40, v35
	v_sub_f32_e32 v43, v40, v36
	v_sub_f32_e32 v40, v40, v37
	v_mul_f32_e32 v41, 0x3fb8aa3b, v41
	v_mul_f32_e32 v42, 0x3fb8aa3b, v42
	v_mul_f32_e32 v43, 0x3fb8aa3b, v43
	v_mul_f32_e32 v45, 0x3fb8aa3b, v40
	v_exp_f32_e32 v40, v41
	v_exp_f32_e32 v41, v42
	v_exp_f32_e32 v42, v43
	v_exp_f32_e32 v43, v45
	v_mul_lo_u32 v45, s27, v92
	v_pk_mul_f32 v[40:41], v[40:41], v[88:89]
	v_pk_mul_f32 v[42:43], v[42:43], v[90:91]
	v_cvt_pk_bf16_f32 v40, v40, v41
	v_cvt_pk_bf16_f32 v41, v42, v43
	v_cndmask_b32_e64 v42, 0, v40, s[0:1]
	v_cmp_gt_i32_e64 s[0:1], 1, v45
	v_lshrrev_b32_e32 v40, 16, v40
	s_nop 0
	v_cndmask_b32_e64 v43, 0, v41, s[0:1]
	v_cmp_gt_i32_e64 s[0:1], s21, v44
	v_lshrrev_b32_e32 v41, 16, v41
	v_mul_lo_u32 v44, s27, v229
	v_cndmask_b32_e64 v40, 0, v40, s[0:1]
	v_cmp_gt_i32_e64 s[0:1], 1, v46
	v_perm_b32 v40, v40, v42, s64
	v_mul_lo_u32 v46, s27, v87
	v_cndmask_b32_e64 v41, 0, v41, s[0:1]
	v_perm_b32 v41, v41, v43, s64
	ds_write_b64 v155, v[40:41] offset:8704
	ds_read_b32 v40, v38 offset:192
	v_cmp_gt_i32_e64 s[0:1], 1, v44
	s_waitcnt lgkmcnt(0)
	v_sub_f32_e32 v41, v40, v34
	v_sub_f32_e32 v42, v40, v35
	v_sub_f32_e32 v43, v40, v36
	v_sub_f32_e32 v40, v40, v37
	v_mul_f32_e32 v41, 0x3fb8aa3b, v41
	v_mul_f32_e32 v42, 0x3fb8aa3b, v42
	v_mul_f32_e32 v43, 0x3fb8aa3b, v43
	v_mul_f32_e32 v45, 0x3fb8aa3b, v40
	v_exp_f32_e32 v40, v41
	v_exp_f32_e32 v41, v42
	v_exp_f32_e32 v42, v43
	v_exp_f32_e32 v43, v45
	v_mul_lo_u32 v45, s27, v98
	v_pk_mul_f32 v[40:41], v[40:41], v[94:95]
	v_pk_mul_f32 v[42:43], v[42:43], v[96:97]
	v_cvt_pk_bf16_f32 v40, v40, v41
	v_cvt_pk_bf16_f32 v41, v42, v43
	v_cndmask_b32_e64 v42, 0, v40, s[0:1]
	v_cmp_gt_i32_e64 s[0:1], 1, v45
	v_lshrrev_b32_e32 v40, 16, v40
	v_mul_lo_u32 v45, s27, v104
	v_cndmask_b32_e64 v43, 0, v41, s[0:1]
	v_cmp_gt_i32_e64 s[0:1], s21, v44
	v_lshrrev_b32_e32 v41, 16, v41
	v_mul_lo_u32 v44, s27, v230
	v_cndmask_b32_e64 v40, 0, v40, s[0:1]
	v_cmp_gt_i32_e64 s[0:1], 1, v46
	v_perm_b32 v40, v40, v42, s64
	v_mul_lo_u32 v46, s27, v93
	v_cndmask_b32_e64 v41, 0, v41, s[0:1]
	v_perm_b32 v41, v41, v43, s64
	ds_write_b64 v155, v[40:41] offset:13056
	ds_read_b32 v43, v38 offset:256
	v_cmp_gt_i32_e64 s[0:1], 1, v44
	s_waitcnt lgkmcnt(0)
	v_sub_f32_e32 v40, v43, v34
	v_sub_f32_e32 v41, v43, v35
	v_mul_f32_e32 v40, 0x3fb8aa3b, v40
	v_mul_f32_e32 v41, 0x3fb8aa3b, v41
	v_exp_f32_e32 v40, v40
	v_exp_f32_e32 v41, v41
	v_sub_f32_e32 v42, v43, v36
	v_sub_f32_e32 v43, v43, v37
	v_mul_f32_e32 v42, 0x3fb8aa3b, v42
	v_mul_f32_e32 v43, 0x3fb8aa3b, v43
	v_exp_f32_e32 v42, v42
	v_exp_f32_e32 v43, v43
	v_pk_mul_f32 v[40:41], v[40:41], v[100:101]
	v_pk_mul_f32 v[42:43], v[42:43], v[102:103]
	v_cvt_pk_bf16_f32 v40, v40, v41
	v_cndmask_b32_e64 v47, 0, v40, s[0:1]
	v_lshrrev_b32_e32 v40, 16, v40
	v_cmp_gt_i32_e64 s[0:1], s21, v44
	v_cvt_pk_bf16_f32 v41, v42, v43
	v_mul_lo_u32 v44, s27, v231
	v_cndmask_b32_e64 v40, 0, v40, s[0:1]
	v_cmp_gt_i32_e64 s[0:1], 1, v45
	v_perm_b32 v40, v40, v47, s64
	v_mul_lo_u32 v45, s27, v110
	v_cndmask_b32_e64 v42, 0, v41, s[0:1]
	v_lshrrev_b32_e32 v41, 16, v41
	v_cmp_gt_i32_e64 s[0:1], 1, v46
	v_mul_lo_u32 v46, s27, v99
	s_nop 0
	v_cndmask_b32_e64 v41, 0, v41, s[0:1]
	v_perm_b32 v41, v41, v42, s64
	ds_write_b64 v155, v[40:41] offset:17408
	ds_read_b32 v43, v38 offset:320
	v_cmp_gt_i32_e64 s[0:1], 1, v44
	s_waitcnt lgkmcnt(0)
	v_sub_f32_e32 v40, v43, v34
	v_sub_f32_e32 v41, v43, v35
	v_mul_f32_e32 v40, 0x3fb8aa3b, v40
	v_mul_f32_e32 v41, 0x3fb8aa3b, v41
	v_exp_f32_e32 v40, v40
	v_exp_f32_e32 v41, v41
	v_sub_f32_e32 v42, v43, v36
	v_sub_f32_e32 v43, v43, v37
	v_mul_f32_e32 v42, 0x3fb8aa3b, v42
	v_mul_f32_e32 v43, 0x3fb8aa3b, v43
	v_exp_f32_e32 v42, v42
	v_exp_f32_e32 v43, v43
	v_pk_mul_f32 v[40:41], v[40:41], v[106:107]
	v_pk_mul_f32 v[42:43], v[42:43], v[108:109]
	v_cvt_pk_bf16_f32 v40, v40, v41
	v_cndmask_b32_e64 v47, 0, v40, s[0:1]
	v_lshrrev_b32_e32 v40, 16, v40
	v_cmp_gt_i32_e64 s[0:1], s21, v44
	v_cvt_pk_bf16_f32 v41, v42, v43
	v_mul_lo_u32 v44, s27, v232
	v_cndmask_b32_e64 v40, 0, v40, s[0:1]
	v_cmp_gt_i32_e64 s[0:1], 1, v45
	v_perm_b32 v40, v40, v47, s64
	v_mul_lo_u32 v45, s27, v116
	v_cndmask_b32_e64 v42, 0, v41, s[0:1]
	v_lshrrev_b32_e32 v41, 16, v41
	v_cmp_gt_i32_e64 s[0:1], 1, v46
	v_mul_lo_u32 v46, s27, v105
	s_nop 0
	v_cndmask_b32_e64 v41, 0, v41, s[0:1]
	v_perm_b32 v41, v41, v42, s64
	ds_write_b64 v155, v[40:41] offset:21760
	ds_read_b32 v43, v38 offset:384
	v_cmp_gt_i32_e64 s[0:1], 1, v44
	s_waitcnt lgkmcnt(0)
	v_sub_f32_e32 v40, v43, v34
	v_sub_f32_e32 v41, v43, v35
	v_mul_f32_e32 v40, 0x3fb8aa3b, v40
	v_mul_f32_e32 v41, 0x3fb8aa3b, v41
	v_exp_f32_e32 v40, v40
	v_exp_f32_e32 v41, v41
	v_sub_f32_e32 v42, v43, v36
	v_sub_f32_e32 v43, v43, v37
	v_mul_f32_e32 v42, 0x3fb8aa3b, v42
	v_mul_f32_e32 v43, 0x3fb8aa3b, v43
	v_exp_f32_e32 v42, v42
	v_exp_f32_e32 v43, v43
	v_pk_mul_f32 v[40:41], v[40:41], v[112:113]
	v_pk_mul_f32 v[42:43], v[42:43], v[114:115]
	v_cvt_pk_bf16_f32 v40, v40, v41
	v_cndmask_b32_e64 v47, 0, v40, s[0:1]
	v_lshrrev_b32_e32 v40, 16, v40
	v_cmp_gt_i32_e64 s[0:1], s21, v44
	v_cvt_pk_bf16_f32 v41, v42, v43
	v_mul_lo_u32 v44, s27, v234
	v_cndmask_b32_e64 v40, 0, v40, s[0:1]
	v_cmp_gt_i32_e64 s[0:1], 1, v45
	v_perm_b32 v40, v40, v47, s64
	v_mul_lo_u32 v45, s27, v117
	v_cndmask_b32_e64 v42, 0, v41, s[0:1]
	v_lshrrev_b32_e32 v41, 16, v41
	v_cmp_gt_i32_e64 s[0:1], 1, v46
	s_nop 1
	v_cndmask_b32_e64 v41, 0, v41, s[0:1]
	v_perm_b32 v41, v41, v42, s64
	ds_write_b64 v155, v[40:41] offset:26112
	ds_read_b32 v40, v38 offset:448
	v_mul_lo_u32 v41, s27, v233
	v_cmp_gt_i32_e64 s[0:1], 1, v41
	v_mul_lo_u32 v42, s27, v111
	s_waitcnt lgkmcnt(0)
	v_sub_f32_e32 v34, v40, v34
	v_sub_f32_e32 v35, v40, v35
	v_mul_f32_e32 v34, 0x3fb8aa3b, v34
	v_mul_f32_e32 v35, 0x3fb8aa3b, v35
	v_exp_f32_e32 v34, v34
	v_exp_f32_e32 v35, v35
	v_sub_f32_e32 v36, v40, v36
	v_sub_f32_e32 v37, v40, v37
	v_mul_f32_e32 v36, 0x3fb8aa3b, v36
	v_mul_f32_e32 v37, 0x3fb8aa3b, v37
	v_exp_f32_e32 v36, v36
	v_exp_f32_e32 v37, v37
	v_pk_mul_f32 v[34:35], v[34:35], v[118:119]
	v_mul_lo_u32 v40, s27, v122
	v_cvt_pk_bf16_f32 v34, v34, v35
	v_pk_mul_f32 v[36:37], v[36:37], v[120:121]
	v_cndmask_b32_e64 v43, 0, v34, s[0:1]
	v_lshrrev_b32_e32 v34, 16, v34
	v_cmp_gt_i32_e64 s[0:1], s21, v41
	v_cvt_pk_bf16_f32 v35, v36, v37
	s_nop 0
	v_cndmask_b32_e64 v34, 0, v34, s[0:1]
	v_cmp_gt_i32_e64 s[0:1], 1, v40
	v_perm_b32 v34, v34, v43, s64
	s_nop 0
	v_cndmask_b32_e64 v36, 0, v35, s[0:1]
	v_lshrrev_b32_e32 v35, 16, v35
	v_cmp_gt_i32_e64 s[0:1], 1, v42
	s_nop 1
	v_cndmask_b32_e64 v35, 0, v35, s[0:1]
	v_perm_b32 v35, v35, v36, s64
	ds_write_b64 v155, v[34:35] offset:30464
	ds_read_b128 v[34:37], v39 offset:64
	ds_read_b32 v39, v38
	v_cmp_gt_i32_e64 s[0:1], 1, v44
	s_waitcnt lgkmcnt(0)
	v_sub_f32_e32 v40, v39, v34
	v_sub_f32_e32 v41, v39, v35
	v_mul_f32_e32 v40, 0x3fb8aa3b, v40
	v_mul_f32_e32 v41, 0x3fb8aa3b, v41
	v_exp_f32_e32 v40, v40
	v_exp_f32_e32 v41, v41
	v_sub_f32_e32 v42, v39, v36
	v_sub_f32_e32 v39, v39, v37
	v_mul_f32_e32 v42, 0x3fb8aa3b, v42
	v_mul_f32_e32 v39, 0x3fb8aa3b, v39
	v_exp_f32_e32 v42, v42
	v_exp_f32_e32 v43, v39
	v_pk_mul_f32 v[40:41], v[40:41], v[124:125]
	v_mul_lo_u32 v39, s27, v128
	v_cvt_pk_bf16_f32 v40, v40, v41
	v_pk_mul_f32 v[42:43], v[42:43], v[126:127]
	v_cndmask_b32_e64 v46, 0, v40, s[0:1]
	v_lshrrev_b32_e32 v40, 16, v40
	v_cmp_gt_i32_e64 s[0:1], s21, v44
	v_cvt_pk_bf16_f32 v41, v42, v43
	v_mul_lo_u32 v44, s27, v235
	v_cndmask_b32_e64 v40, 0, v40, s[0:1]
	v_cmp_gt_i32_e64 s[0:1], 1, v39
	v_perm_b32 v40, v40, v46, s64
	s_nop 0
	v_cndmask_b32_e64 v39, 0, v41, s[0:1]
	v_lshrrev_b32_e32 v41, 16, v41
	v_cmp_gt_i32_e64 s[0:1], 1, v45
	v_mul_lo_u32 v45, s27, v123
	s_nop 0
	v_cndmask_b32_e64 v41, 0, v41, s[0:1]
	v_perm_b32 v41, v41, v39, s64
	ds_write_b64 v155, v[40:41] offset:32
	ds_read_b32 v39, v38 offset:64
	s_waitcnt lgkmcnt(0)
	v_sub_f32_e32 v40, v39, v34
	v_sub_f32_e32 v41, v39, v35
	v_sub_f32_e32 v42, v39, v36
	v_sub_f32_e32 v39, v39, v37
	v_mul_f32_e32 v40, 0x3fb8aa3b, v40
	v_mul_f32_e32 v41, 0x3fb8aa3b, v41
	v_mul_f32_e32 v42, 0x3fb8aa3b, v42
	v_mul_f32_e32 v39, 0x3fb8aa3b, v39
	v_exp_f32_e32 v40, v40
	v_exp_f32_e32 v41, v41
	v_exp_f32_e32 v42, v42
	v_exp_f32_e32 v43, v39
	v_pk_mul_f32 v[40:41], v[40:41], v[142:143]
	s_nop 0
	v_cvt_pk_bf16_f32 v39, v40, v41
	v_pk_mul_f32 v[42:43], v[42:43], v[144:145]
	v_cndmask_b32_e64 v40, 0, v39, s[4:5]
	v_cvt_pk_bf16_f32 v41, v42, v43
	v_lshrrev_b32_e32 v39, 16, v39
	v_cndmask_b32_e32 v42, 0, v41, vcc
	v_lshrrev_b32_e32 v41, 16, v41
	v_cndmask_b32_e64 v39, 0, v39, s[8:9]
	v_cndmask_b32_e64 v41, 0, v41, s[6:7]
	v_perm_b32 v41, v41, v42, s64
	v_perm_b32 v40, v39, v40, s64
	ds_write_b64 v155, v[40:41] offset:4384
	ds_read_b32 v39, v38 offset:128
	v_cmp_gt_i32_e32 vcc, 1, v44
	s_waitcnt lgkmcnt(0)
	v_sub_f32_e32 v40, v39, v34
	v_sub_f32_e32 v41, v39, v35
	v_mul_f32_e32 v40, 0x3fb8aa3b, v40
	v_mul_f32_e32 v41, 0x3fb8aa3b, v41
	v_exp_f32_e32 v40, v40
	v_exp_f32_e32 v41, v41
	v_sub_f32_e32 v42, v39, v36
	v_sub_f32_e32 v39, v39, v37
	v_mul_f32_e32 v42, 0x3fb8aa3b, v42
	v_mul_f32_e32 v39, 0x3fb8aa3b, v39
	v_exp_f32_e32 v42, v42
	v_exp_f32_e32 v43, v39
	v_pk_mul_f32 v[40:41], v[40:41], v[146:147]
	v_mul_lo_u32 v39, s27, v134
	v_cvt_pk_bf16_f32 v40, v40, v41
	v_pk_mul_f32 v[42:43], v[42:43], v[148:149]
	v_cndmask_b32_e32 v46, 0, v40, vcc
	v_lshrrev_b32_e32 v40, 16, v40
	v_cmp_gt_i32_e32 vcc, s21, v44
	v_cvt_pk_bf16_f32 v41, v42, v43
	v_mul_lo_u32 v44, s27, v236
	v_cndmask_b32_e32 v40, 0, v40, vcc
	v_cmp_gt_i32_e32 vcc, 1, v39
	v_perm_b32 v40, v40, v46, s64
	s_nop 0
	v_cndmask_b32_e32 v39, 0, v41, vcc
	v_lshrrev_b32_e32 v41, 16, v41
	v_cmp_gt_i32_e32 vcc, 1, v45
	v_mul_lo_u32 v45, s27, v129
	s_nop 0
	v_cndmask_b32_e32 v41, 0, v41, vcc
	v_perm_b32 v41, v41, v39, s64
	ds_write_b64 v155, v[40:41] offset:8736
	ds_read_b32 v39, v38 offset:192
	v_cmp_gt_i32_e32 vcc, 1, v44
	s_waitcnt lgkmcnt(0)
	v_sub_f32_e32 v40, v39, v34
	v_sub_f32_e32 v41, v39, v35
	v_mul_f32_e32 v40, 0x3fb8aa3b, v40
	v_mul_f32_e32 v41, 0x3fb8aa3b, v41
	v_exp_f32_e32 v40, v40
	v_exp_f32_e32 v41, v41
	v_sub_f32_e32 v42, v39, v36
	v_sub_f32_e32 v39, v39, v37
	v_mul_f32_e32 v42, 0x3fb8aa3b, v42
	v_mul_f32_e32 v39, 0x3fb8aa3b, v39
	v_exp_f32_e32 v42, v42
	v_exp_f32_e32 v43, v39
	v_pk_mul_f32 v[40:41], v[40:41], v[150:151]
	v_mul_lo_u32 v39, s27, v154
	v_cvt_pk_bf16_f32 v40, v40, v41
	v_pk_mul_f32 v[42:43], v[42:43], v[152:153]
	v_cndmask_b32_e32 v46, 0, v40, vcc
	v_lshrrev_b32_e32 v40, 16, v40
	v_cmp_gt_i32_e32 vcc, s21, v44
	v_cvt_pk_bf16_f32 v41, v42, v43
	v_mul_lo_u32 v44, s27, v237
	v_cndmask_b32_e32 v40, 0, v40, vcc
	v_cmp_gt_i32_e32 vcc, 1, v39
	v_perm_b32 v40, v40, v46, s64
	s_nop 0
	v_cndmask_b32_e32 v39, 0, v41, vcc
	v_lshrrev_b32_e32 v41, 16, v41
	v_cmp_gt_i32_e32 vcc, 1, v45
	v_mul_lo_u32 v45, s27, v133
	s_nop 0
	v_cndmask_b32_e32 v41, 0, v41, vcc
	v_perm_b32 v41, v41, v39, s64
	ds_write_b64 v155, v[40:41] offset:13088
	ds_read_b32 v39, v38 offset:256
	v_cmp_gt_i32_e32 vcc, 1, v44
	s_waitcnt lgkmcnt(0)
	v_sub_f32_e32 v40, v39, v34
	v_sub_f32_e32 v41, v39, v35
	v_mul_f32_e32 v40, 0x3fb8aa3b, v40
	v_mul_f32_e32 v41, 0x3fb8aa3b, v41
	v_exp_f32_e32 v40, v40
	v_exp_f32_e32 v41, v41
	v_sub_f32_e32 v42, v39, v36
	v_sub_f32_e32 v39, v39, v37
	v_mul_f32_e32 v42, 0x3fb8aa3b, v42
	v_mul_f32_e32 v39, 0x3fb8aa3b, v39
	v_exp_f32_e32 v42, v42
	v_exp_f32_e32 v43, v39
	v_pk_mul_f32 v[40:41], v[40:41], v[156:157]
	v_mul_lo_u32 v39, s27, v160
	v_cvt_pk_bf16_f32 v40, v40, v41
	v_pk_mul_f32 v[42:43], v[42:43], v[158:159]
	v_cndmask_b32_e32 v46, 0, v40, vcc
	v_lshrrev_b32_e32 v40, 16, v40
	v_cmp_gt_i32_e32 vcc, s21, v44
	v_cvt_pk_bf16_f32 v41, v42, v43
	v_mul_lo_u32 v44, s27, v238
	v_cndmask_b32_e32 v40, 0, v40, vcc
	v_cmp_gt_i32_e32 vcc, 1, v39
	v_perm_b32 v40, v40, v46, s64
	s_nop 0
	v_cndmask_b32_e32 v39, 0, v41, vcc
	v_lshrrev_b32_e32 v41, 16, v41
	v_cmp_gt_i32_e32 vcc, 1, v45
	v_mul_lo_u32 v45, s27, v137
	s_nop 0
	v_cndmask_b32_e32 v41, 0, v41, vcc
	v_perm_b32 v41, v41, v39, s64
	ds_write_b64 v155, v[40:41] offset:17440
	ds_read_b32 v39, v38 offset:320
	v_cmp_gt_i32_e32 vcc, 1, v44
	s_waitcnt lgkmcnt(0)
	v_sub_f32_e32 v40, v39, v34
	v_sub_f32_e32 v41, v39, v35
	v_mul_f32_e32 v40, 0x3fb8aa3b, v40
	v_mul_f32_e32 v41, 0x3fb8aa3b, v41
	v_exp_f32_e32 v40, v40
	v_exp_f32_e32 v41, v41
	v_sub_f32_e32 v42, v39, v36
	v_sub_f32_e32 v39, v39, v37
	v_mul_f32_e32 v42, 0x3fb8aa3b, v42
	v_mul_f32_e32 v39, 0x3fb8aa3b, v39
	v_exp_f32_e32 v42, v42
	v_exp_f32_e32 v43, v39
	v_pk_mul_f32 v[40:41], v[40:41], v[162:163]
	v_mul_lo_u32 v39, s27, v166
	v_cvt_pk_bf16_f32 v40, v40, v41
	v_pk_mul_f32 v[42:43], v[42:43], v[164:165]
	v_cndmask_b32_e32 v46, 0, v40, vcc
	v_lshrrev_b32_e32 v40, 16, v40
	v_cmp_gt_i32_e32 vcc, s21, v44
	v_cvt_pk_bf16_f32 v41, v42, v43
	v_mul_lo_u32 v44, s27, v239
	v_cndmask_b32_e32 v40, 0, v40, vcc
	v_cmp_gt_i32_e32 vcc, 1, v39
	v_perm_b32 v40, v40, v46, s64
	s_nop 0
	v_cndmask_b32_e32 v39, 0, v41, vcc
	v_lshrrev_b32_e32 v41, 16, v41
	v_cmp_gt_i32_e32 vcc, 1, v45
	v_mul_lo_u32 v45, s27, v139
	s_nop 0
	v_cndmask_b32_e32 v41, 0, v41, vcc
	v_perm_b32 v41, v41, v39, s64
	ds_write_b64 v155, v[40:41] offset:21792
	ds_read_b32 v39, v38 offset:384
	v_cmp_gt_i32_e32 vcc, 1, v44
	s_waitcnt lgkmcnt(0)
	v_sub_f32_e32 v40, v39, v34
	v_sub_f32_e32 v41, v39, v35
	v_mul_f32_e32 v40, 0x3fb8aa3b, v40
	v_mul_f32_e32 v41, 0x3fb8aa3b, v41
	v_exp_f32_e32 v40, v40
	v_exp_f32_e32 v41, v41
	v_sub_f32_e32 v42, v39, v36
	v_sub_f32_e32 v39, v39, v37
	v_mul_f32_e32 v42, 0x3fb8aa3b, v42
	v_mul_f32_e32 v39, 0x3fb8aa3b, v39
	v_exp_f32_e32 v42, v42
	v_exp_f32_e32 v43, v39
	v_pk_mul_f32 v[40:41], v[40:41], v[168:169]
	v_mul_lo_u32 v39, s27, v172
	v_cvt_pk_bf16_f32 v40, v40, v41
	v_pk_mul_f32 v[42:43], v[42:43], v[170:171]
	v_cndmask_b32_e32 v46, 0, v40, vcc
	v_lshrrev_b32_e32 v40, 16, v40
	v_cmp_gt_i32_e32 vcc, s21, v44
	v_cvt_pk_bf16_f32 v41, v42, v43
	s_nop 0
	v_cndmask_b32_e32 v40, 0, v40, vcc
	v_cmp_gt_i32_e32 vcc, 1, v39
	v_perm_b32 v40, v40, v46, s64
	s_nop 0
	v_cndmask_b32_e32 v39, 0, v41, vcc
	v_lshrrev_b32_e32 v41, 16, v41
	v_cmp_gt_i32_e32 vcc, 1, v45
	s_nop 1
	v_cndmask_b32_e32 v41, 0, v41, vcc
	v_perm_b32 v41, v41, v39, s64
	ds_write_b64 v155, v[40:41] offset:26144
	ds_read_b32 v38, v38 offset:448
	v_mul_lo_u32 v39, s27, v240
	v_cmp_gt_i32_e32 vcc, 1, v39
	v_mul_lo_u32 v40, s27, v141
	s_waitcnt lgkmcnt(0)
	v_sub_f32_e32 v34, v38, v34
	v_sub_f32_e32 v35, v38, v35
	v_mul_f32_e32 v34, 0x3fb8aa3b, v34
	v_mul_f32_e32 v35, 0x3fb8aa3b, v35
	v_exp_f32_e32 v34, v34
	v_exp_f32_e32 v35, v35
	v_sub_f32_e32 v36, v38, v36
	v_sub_f32_e32 v37, v38, v37
	v_mul_f32_e32 v36, 0x3fb8aa3b, v36
	v_mul_f32_e32 v37, 0x3fb8aa3b, v37
	v_exp_f32_e32 v36, v36
	v_exp_f32_e32 v37, v37
	v_pk_mul_f32 v[34:35], v[34:35], v[174:175]
	v_mul_lo_u32 v38, s27, v178
	v_cvt_pk_bf16_f32 v34, v34, v35
	v_pk_mul_f32 v[36:37], v[36:37], v[176:177]
	v_cndmask_b32_e32 v41, 0, v34, vcc
	v_lshrrev_b32_e32 v34, 16, v34
	v_cmp_gt_i32_e32 vcc, s21, v39
	v_cvt_pk_bf16_f32 v35, v36, v37
	s_nop 0
	v_cndmask_b32_e32 v34, 0, v34, vcc
	v_cmp_gt_i32_e32 vcc, 1, v38
	v_perm_b32 v34, v34, v41, s64
	s_nop 0
	v_cndmask_b32_e32 v36, 0, v35, vcc
	v_lshrrev_b32_e32 v35, 16, v35
	v_cmp_gt_i32_e32 vcc, 1, v40
	s_nop 1
	v_cndmask_b32_e32 v35, 0, v35, vcc
	v_perm_b32 v35, v35, v36, s64
	ds_write_b64 v155, v[34:35] offset:30496
	v_cndmask_b32_e64 v34, v220, 0, s[2:3]
	v_cmp_le_i32_e32 vcc, v34, v189
	s_waitcnt lgkmcnt(0)
	s_barrier
	s_and_saveexec_b64 s[0:1], vcc
	s_cbranch_execz .LBB0_187
	v_lshlrev_b32_e32 v35, 6, v34
	v_lshl_or_b32 v36, s17, 9, v241
	v_add_u32_e32 v242, -1, v34
	v_add_u32_e32 v243, v130, v35
	v_lshl_add_u32 v244, v34, 7, v36
	v_add_u32_e32 v245, v188, v35
	s_mov_b64 s[4:5], 0

.LBB0_323:
	s_and_b64 vcc, exec, s[2:3]
	s_cbranch_vccz .LBB0_327
	s_add_i32 s2, s14, 0xfde0
	s_and_b32 s3, s2, 0xffff
	s_mul_i32 s3, s3, 0xf0f1
	s_lshr_b32 s4, s3, 20
	s_mul_i32 s5, s4, 17
	s_sub_i32 s5, s2, s5
	v_mov_b32_e32 v1, v0
	s_and_b32 s6, s5, 0xffff
	s_lshr_b32 s2, s3, 12
	s_and_b32 s3, s2, 0xff00
	s_waitcnt vmcnt(0)
	v_and_b32_e32 v10, 15, v1
	v_and_b32_e32 v2, 0xffffffcf, v1
	s_mul_i32 s2, s4, 0x4400
	s_lshl_b32 s6, s6, 10
	s_lshl_b32 s88, s4, 18
	v_ashrrev_i32_e32 v3, 31, v2
	v_lshlrev_b32_e32 v118, 4, v10
	s_add_i32 s4, s2, s6
	v_lshlrev_b64 v[4:5], 10, v[2:3]
	v_and_b32_e32 v11, 48, v1
	v_or_b32_e32 v8, s4, v118
	v_lshl_or_b32 v3, v8, 5, v11
	v_lshl_add_u64 v[4:5], s[88:89], 0, v[4:5]
	v_or_b32_e32 v130, 0x6000, v3
	v_or_b32_e32 v4, v4, v11
	v_lshl_add_u64 v[70:71], s[86:87], 0, v[130:131]
	v_or_b32_e32 v130, 0x4000, v3
	v_lshl_add_u64 v[78:79], s[86:87], 0, v[4:5]
	v_or_b32_e32 v4, 16, v2
	v_or_b32_e32 v2, 32, v2
	v_lshl_add_u64 v[72:73], s[86:87], 0, v[130:131]
	v_or_b32_e32 v130, 0x2000, v3
	v_ashrrev_i32_e32 v3, 31, v2
	v_or_b32_e32 v6, 48, v1
	v_lshlrev_b64 v[2:3], 10, v[2:3]
	v_ashrrev_i32_e32 v7, 31, v6
	v_lshl_add_u64 v[2:3], s[88:89], 0, v[2:3]
	v_lshlrev_b64 v[6:7], 10, v[6:7]
	v_or_b32_e32 v2, v2, v11
	s_lshl_b32 s4, s5, 19
	v_lshl_add_u64 v[82:83], s[86:87], 0, v[2:3]
	v_lshl_add_u64 v[2:3], s[88:89], 0, v[6:7]
	s_or_b32 s3, s4, s3
	v_lshl_add_u64 v[74:75], s[86:87], 0, v[130:131]
	v_or_b32_e32 v2, v2, v11
	v_lshl_add_u32 v130, v10, 13, s3
	v_lshl_add_u64 v[84:85], s[86:87], 0, v[2:3]
	v_lshlrev_b64 v[2:3], 1, v[130:131]
	v_or_b32_e32 v2, v2, v11
	v_lshl_add_u64 v[86:87], s[86:87], 0, v[2:3]
	v_add_u32_e32 v2, 0x20000, v130
	v_mov_b32_e32 v3, v131
	v_lshlrev_b64 v[2:3], 1, v[2:3]
	v_or_b32_e32 v2, v2, v11
	v_lshl_add_u64 v[88:89], s[86:87], 0, v[2:3]
	v_or_b32_e32 v2, 0x40000, v130
	v_mov_b32_e32 v3, v131
	v_ashrrev_i32_e32 v5, 31, v4
	v_lshlrev_b64 v[2:3], 1, v[2:3]
	v_mov_b32_e32 v9, v131
	v_lshlrev_b64 v[4:5], 10, v[4:5]
	v_or_b32_e32 v2, v2, v11
	v_add_u32_e32 v130, 0x60000, v130
	v_lshlrev_b64 v[8:9], 5, v[8:9]
	v_lshl_add_u64 v[4:5], s[88:89], 0, v[4:5]
	v_lshl_add_u64 v[90:91], s[86:87], 0, v[2:3]
	v_lshlrev_b64 v[2:3], 1, v[130:131]
	v_or_b32_e32 v8, v8, v11
	v_or_b32_e32 v4, v4, v11
	v_or_b32_e32 v2, v2, v11
	v_mov_b32_e32 v18, 0
	v_lshrrev_b32_e32 v119, 4, v1
	v_lshl_add_u64 v[76:77], s[86:87], 0, v[8:9]
	v_lshl_add_u64 v[80:81], s[86:87], 0, v[4:5]
	v_lshl_add_u64 v[92:93], s[86:87], 0, v[2:3]
	s_lshr_b32 s62, s88, 18
	s_mul_i32 s64, s62, 0x88000
	s_and_b32 s65, s5, 0xffff
	s_lshl_b32 s65, s65, 15
	s_add_u32 s64, s64, s65
	s_add_u32 s98, s86, s64
	s_addc_u32 s99, s87, 0
	s_add_u32 s98, s98, 0x2bf1100
	s_addc_u32 s99, s99, 0
	s_and_b32 s64, s5, 0xffff
	s_lshl_b32 s64, s64, 20
	s_lshl_b32 s65, s62, 9
	s_add_u32 s64, s64, s65
	s_add_u32 s62, s86, s64
	s_addc_u32 s63, s87, 0
	s_add_u32 s62, s62, 0x80f1100
	s_addc_u32 s63, s63, 0
	v_lshrrev_b32_e32 v226, 6, v1
	v_and_b32_e32 v227, 31, v1
	v_lshlrev_b32_e32 v227, 4, v227
	v_lshl_add_u32 v228, v226, 9, v227
	v_lshl_add_u32 v229, v226, 14, v227
	v_and_b32_e32 v230, 32, v1
	v_cmp_ne_u32_e32 vcc, 0, v230
	v_mov_b32_e32 v231, s98
	v_mov_b32_e32 v232, s99
	v_mov_b32_e32 v233, s62
	v_mov_b32_e32 v234, s63
	v_cndmask_b32_e32 v228, v228, v229, vcc
	v_cndmask_b32_e32 v224, v231, v233, vcc
	v_cndmask_b32_e32 v225, v232, v234, vcc
	v_mov_b32_e32 v229, 0
	v_lshl_add_u64 v[224:225], v[224:225], 0, v[228:229]
	v_mov_b32_e32 v230, 0x800
	v_mov_b32_e32 v231, 0x10000
	v_cndmask_b32_e32 v228, v230, v231, vcc
	v_and_b32_e32 v227, 63, v1
	v_lshlrev_b32_e32 v227, 4, v227
	s_movk_i32 s64, 0x410
	v_mad_u32_u24 v226, v226, s64, v227
	v_and_b32_e32 v222, 15, v1
	v_mul_u32_u24_e32 v222, 0x410, v222
	v_bfe_u32 v227, v1, 4, 2
	v_lshl_add_u32 v222, v227, 4, v222
	global_load_dwordx4 v[2:5], v[224:225], off nt
	v_lshl_add_u64 v[224:225], v[224:225], 0, v[228:229]
	global_load_dwordx4 v[6:9], v[224:225], off nt
	v_lshl_add_u64 v[224:225], v[224:225], 0, v[228:229]
	global_load_dwordx4 v[10:13], v[224:225], off nt
	v_lshl_add_u64 v[224:225], v[224:225], 0, v[228:229]
	global_load_dwordx4 v[14:17], v[224:225], off nt
	v_lshl_add_u64 v[224:225], v[224:225], 0, v[228:229]
	global_load_dwordx4 v[20:23], v[224:225], off nt
	v_lshl_add_u64 v[224:225], v[224:225], 0, v[228:229]
	global_load_dwordx4 v[24:27], v[224:225], off nt
	v_lshl_add_u64 v[224:225], v[224:225], 0, v[228:229]
	global_load_dwordx4 v[28:31], v[224:225], off nt
	v_lshl_add_u64 v[224:225], v[224:225], 0, v[228:229]
	global_load_dwordx4 v[32:35], v[224:225], off nt
	v_lshl_add_u64 v[224:225], v[224:225], 0, v[228:229]
	global_load_dwordx4 v[36:39], v[224:225], off nt
	v_lshl_add_u64 v[224:225], v[224:225], 0, v[228:229]
	global_load_dwordx4 v[40:43], v[224:225], off nt
	v_lshl_add_u64 v[224:225], v[224:225], 0, v[228:229]
	global_load_dwordx4 v[44:47], v[224:225], off nt
	v_lshl_add_u64 v[224:225], v[224:225], 0, v[228:229]
	global_load_dwordx4 v[48:51], v[224:225], off nt
	v_lshl_add_u64 v[224:225], v[224:225], 0, v[228:229]
	global_load_dwordx4 v[52:55], v[224:225], off nt
	v_lshl_add_u64 v[224:225], v[224:225], 0, v[228:229]
	global_load_dwordx4 v[56:59], v[224:225], off nt
	v_lshl_add_u64 v[224:225], v[224:225], 0, v[228:229]
	global_load_dwordx4 v[60:63], v[224:225], off nt
	v_lshl_add_u64 v[224:225], v[224:225], 0, v[228:229]
	global_load_dwordx4 v[64:67], v[224:225], off nt
	s_waitcnt vmcnt(0)
	ds_write_b128 v226, v[2:5]
	ds_write_b128 v226, v[6:9] offset:4160
	ds_write_b128 v226, v[10:13] offset:8320
	ds_write_b128 v226, v[14:17] offset:12480
	ds_write_b128 v226, v[20:23] offset:16640
	ds_write_b128 v226, v[24:27] offset:20800
	ds_write_b128 v226, v[28:31] offset:24960
	ds_write_b128 v226, v[32:35] offset:29120
	ds_write_b128 v226, v[36:39] offset:33280
	ds_write_b128 v226, v[40:43] offset:37440
	ds_write_b128 v226, v[44:47] offset:41600
	ds_write_b128 v226, v[48:51] offset:45760
	ds_write_b128 v226, v[52:55] offset:49920
	ds_write_b128 v226, v[56:59] offset:54080
	ds_write_b128 v226, v[60:63] offset:58240
	ds_write_b128 v226, v[64:67] offset:62400
	s_waitcnt lgkmcnt(0)
	s_barrier
	s_mov_b32 s3, 0
	s_mov_b64 s[4:5], 0
	v_mov_b32_e32 v19, v18
	v_mov_b32_e32 v20, v18
	v_mov_b32_e32 v21, v18
	v_mov_b32_e32 v22, v18
	v_mov_b32_e32 v23, v18
	v_mov_b32_e32 v24, v18
	v_mov_b32_e32 v25, v18
	v_mov_b32_e32 v26, v18
	v_mov_b32_e32 v27, v18
	v_mov_b32_e32 v28, v18
	v_mov_b32_e32 v29, v18
	v_mov_b32_e32 v30, v18
	v_mov_b32_e32 v31, v18
	v_mov_b32_e32 v32, v18
	v_mov_b32_e32 v33, v18
	v_mov_b32_e32 v34, v18
	v_mov_b32_e32 v35, v18
	v_mov_b32_e32 v36, v18
	v_mov_b32_e32 v37, v18
	v_mov_b32_e32 v38, v18
	v_mov_b32_e32 v39, v18
	v_mov_b32_e32 v40, v18
	v_mov_b32_e32 v41, v18
	v_mov_b32_e32 v42, v18
	v_mov_b32_e32 v43, v18
	v_mov_b32_e32 v44, v18
	v_mov_b32_e32 v45, v18
	v_mov_b32_e32 v46, v18
	v_mov_b32_e32 v47, v18
	v_mov_b32_e32 v48, v18
	v_mov_b32_e32 v49, v18
	v_mov_b32_e32 v50, v18
	v_mov_b32_e32 v51, v18
	v_mov_b32_e32 v52, v18
	v_mov_b32_e32 v53, v18
	v_mov_b32_e32 v54, v18
	v_mov_b32_e32 v55, v18
	v_mov_b32_e32 v56, v18
	v_mov_b32_e32 v57, v18
	v_mov_b32_e32 v58, v18
	v_mov_b32_e32 v59, v18
	v_mov_b32_e32 v60, v18
	v_mov_b32_e32 v61, v18
	v_mov_b32_e32 v62, v18
	v_mov_b32_e32 v63, v18
	v_mov_b32_e32 v64, v18
	v_mov_b32_e32 v65, v18
	v_mov_b32_e32 v14, v18
	v_mov_b32_e32 v15, v18
	v_mov_b32_e32 v16, v18
	v_mov_b32_e32 v17, v18
	v_mov_b32_e32 v10, v18
	v_mov_b32_e32 v11, v18
	v_mov_b32_e32 v12, v18
	v_mov_b32_e32 v13, v18
	v_mov_b32_e32 v6, v18
	v_mov_b32_e32 v7, v18
	v_mov_b32_e32 v8, v18
	v_mov_b32_e32 v9, v18
	v_mov_b32_e32 v2, v18
	v_mov_b32_e32 v3, v18
	v_mov_b32_e32 v4, v18
	v_mov_b32_e32 v5, v18
	s_mov_b64 s[0:1], 0x2bf1100
	s_mov_b32 s7, 0x9b71000
	s_mov_b64 s[8:9], 0x80f0f00
	s_mov_b64 s[10:11], 0x2bf1140
	s_mov_b64 s[16:17], 0x80f0f40

.LBB0_457:
	s_cmp_ge_i32 s21, s16
	s_mov_b64 s[0:1], -1
	s_cbranch_scc0 .LBB0_543
	v_readlane_b32 s0, v254, 52
	s_cmp_ge_i32 s21, s0
	s_mov_b64 s[0:1], -1
	s_cbranch_scc0 .LBB0_540
	s_sub_i32 s88, s21, s16
	v_readlane_b32 s0, v254, 56
	s_cmp_ge_u32 s21, s0
	s_mov_b64 s[0:1], -1
	s_cbranch_scc0 .LBB0_535
	s_add_i32 s0, s88, 0xf5e0
	s_sext_i32_i16 s1, s0
	s_mulk_i32 s1, 0x2aab
	s_lshr_b32 s2, s1, 31
	s_ashr_i32 s1, s1, 18
	s_add_i32 s90, s1, s2
	s_mul_i32 s1, s90, 24
	v_mov_b32_e32 v1, v0
	s_sub_i32 s0, s0, s1
	s_sext_i32_i16 s91, s0
	v_lshlrev_b32_e32 v76, 3, v1
	s_lshl_b32 s0, s91, 6
	v_and_b32_e32 v78, 56, v76
	v_or_b32_e32 v64, s0, v78
	v_readlane_b32 s2, v254, 58
	v_ashrrev_i32_e32 v65, 31, v64
	v_readlane_b32 s3, v254, 59
	v_ashrrev_i32_e32 v77, 3, v1
	s_cmpk_gt_i32 s88, 0x161f
	s_waitcnt vmcnt(0)
	v_lshl_add_u64 v[2:3], v[64:65], 2, s[2:3]
	global_load_dwordx4 v[6:9], v[2:3], off offset:16
	s_nop 0
	global_load_dwordx4 v[2:5], v[2:3], off
	s_mov_b64 s[2:3], -1
	v_lshlrev_b32_e32 v130, 1, v78
	s_cbranch_scc1 .LBB0_496
	s_lshl_b32 s1, s90, 1
	s_and_b32 s5, s1, 62
	s_lshl_b32 s1, s90, 7
	s_and_b32 s4, s1, 0xfffff000
	s_ashr_i32 s1, s0, 31
	s_add_i32 s5, s5, -1
	s_lshl_b64 s[2:3], s[0:1], 1
	v_readlane_b32 s6, v254, 1
	v_readlane_b32 s7, v254, 2
	s_add_u32 s2, s6, s2
	v_ashrrev_i32_e32 v10, 9, v1
	s_addc_u32 s3, s7, s3
	v_add_u32_e32 v11, s5, v10
	v_lshl_add_u64 v[42:43], s[2:3], 0, v[130:131]
	v_cmp_gt_u32_e32 vcc, 64, v11
	v_mov_b32_e32 v10, 0
	v_bfe_u32 v82, v1, 3, 6
	v_mov_b32_e32 v14, 0
	v_mov_b32_e32 v15, 0
	v_mov_b32_e32 v16, 0
	v_mov_b32_e32 v17, 0
	s_waitcnt vmcnt(63) expcnt(7) lgkmcnt(15)
	s_barrier
	v_readlane_b32 s62, v254, 60
	v_readlane_b32 s63, v254, 61
	s_lshl_b32 s64, s91, 8
	s_add_u32 s62, s62, s64
	s_addc_u32 s63, s63, 0
	s_add_u32 s62, s62, -16
	s_addc_u32 s63, s63, -1
	v_lshrrev_b32_e32 v106, 4, v1
	v_mul_u32_u24_e32 v106, 0x1800, v106
	v_and_b32_e32 v107, 15, v1
	v_lshl_add_u32 v106, v107, 4, v106
	s_movk_i32 s64, 0x90
	v_cmp_gt_u32_e64 s[64:65], s64, v1
	s_nop 1
	s_and_saveexec_b64 s[64:65], s[64:65]
	global_load_dwordx4 v[100:103], v106, s[62:63]
	s_or_b64 exec, exec, s[64:65]
	s_and_saveexec_b64 s[2:3], vcc
	s_cbranch_execz .LBB0_463
	v_lshlrev_b32_e32 v11, 6, v11
	v_or3_b32 v11, v11, v82, s4
	s_movk_i32 s1, 0xc00
	v_mul_lo_u32 v12, v11, s1
	v_ashrrev_i32_e32 v13, 31, v12
	v_lshl_add_u64 v[12:13], v[42:43], 0, v[12:13]
	global_load_dwordx4 v[14:17], v[12:13], off nt
.LBB0_463:
	s_or_b64 exec, exec, s[2:3]
	v_add_u32_e32 v18, 0x100, v1
	v_ashrrev_i32_e32 v11, 9, v18
	v_add_u32_e32 v19, s5, v11
	v_cmp_gt_u32_e32 vcc, 64, v19
	v_mov_b32_e32 v11, 0
	v_mov_b32_e32 v12, 0
	v_mov_b32_e32 v13, 0
	s_and_saveexec_b64 s[2:3], vcc
	s_cbranch_execz .LBB0_465
	v_bfe_u32 v10, v18, 3, 6
	v_lshlrev_b32_e32 v11, 6, v19
	v_or3_b32 v10, v11, v10, s4
	s_movk_i32 s1, 0xc00
	v_mul_lo_u32 v10, v10, s1
	v_ashrrev_i32_e32 v11, 31, v10
	v_lshl_add_u64 v[10:11], v[42:43], 0, v[10:11]
	global_load_dwordx4 v[10:13], v[10:11], off nt
.LBB0_465:
	s_or_b64 exec, exec, s[2:3]
	v_add_u32_e32 v18, 0x200, v1
	v_ashrrev_i32_e32 v18, 9, v18
	v_add_u32_e32 v19, s5, v18
	v_cmp_gt_u32_e32 vcc, 64, v19
	v_mov_b32_e32 v18, 0
	v_mov_b32_e32 v22, 0
	v_mov_b32_e32 v23, 0
	v_mov_b32_e32 v24, 0
	v_mov_b32_e32 v25, 0
	s_and_saveexec_b64 s[2:3], vcc
	s_cbranch_execz .LBB0_467
	v_lshlrev_b32_e32 v19, 6, v19
	v_or3_b32 v19, v19, v82, s4
	s_movk_i32 s1, 0xc00
	v_mul_lo_u32 v20, v19, s1
	v_ashrrev_i32_e32 v21, 31, v20
	v_lshl_add_u64 v[20:21], v[42:43], 0, v[20:21]
	global_load_dwordx4 v[22:25], v[20:21], off nt
.LBB0_467:
	s_or_b64 exec, exec, s[2:3]
	v_add_u32_e32 v26, 0x300, v1
	v_ashrrev_i32_e32 v19, 9, v26
	v_add_u32_e32 v27, s5, v19
	v_cmp_gt_u32_e32 vcc, 64, v27
	v_mov_b32_e32 v19, 0
	v_mov_b32_e32 v20, 0
	v_mov_b32_e32 v21, 0
	s_and_saveexec_b64 s[2:3], vcc
	s_cbranch_execz .LBB0_469
	v_bfe_u32 v18, v26, 3, 6
	v_lshlrev_b32_e32 v19, 6, v27
	v_or3_b32 v18, v19, v18, s4
	s_movk_i32 s1, 0xc00
	v_mul_lo_u32 v18, v18, s1
	v_ashrrev_i32_e32 v19, 31, v18
	v_lshl_add_u64 v[18:19], v[42:43], 0, v[18:19]
	global_load_dwordx4 v[18:21], v[18:19], off nt
.LBB0_469:
	s_or_b64 exec, exec, s[2:3]
	v_add_u32_e32 v26, 0x400, v1
	v_ashrrev_i32_e32 v26, 9, v26
	v_add_u32_e32 v27, s5, v26
	v_cmp_gt_u32_e32 vcc, 64, v27
	v_mov_b32_e32 v26, 0
	v_mov_b32_e32 v30, 0
	v_mov_b32_e32 v31, 0
	v_mov_b32_e32 v32, 0
	v_mov_b32_e32 v33, 0
	s_and_saveexec_b64 s[2:3], vcc
	s_cbranch_execz .LBB0_471
	v_lshlrev_b32_e32 v27, 6, v27
	v_or3_b32 v27, v27, v82, s4
	s_movk_i32 s1, 0xc00
	v_mul_lo_u32 v28, v27, s1
	v_ashrrev_i32_e32 v29, 31, v28
	v_lshl_add_u64 v[28:29], v[42:43], 0, v[28:29]
	global_load_dwordx4 v[30:33], v[28:29], off nt
.LBB0_471:
	s_or_b64 exec, exec, s[2:3]
	v_add_u32_e32 v34, 0x500, v1
	v_ashrrev_i32_e32 v27, 9, v34
	v_add_u32_e32 v35, s5, v27
	v_cmp_gt_u32_e32 vcc, 64, v35
	v_mov_b32_e32 v27, 0
	v_mov_b32_e32 v28, 0
	v_mov_b32_e32 v29, 0
	s_and_saveexec_b64 s[2:3], vcc
	s_cbranch_execz .LBB0_473
	v_bfe_u32 v26, v34, 3, 6
	v_lshlrev_b32_e32 v27, 6, v35
	v_or3_b32 v26, v27, v26, s4
	s_movk_i32 s1, 0xc00
	v_mul_lo_u32 v26, v26, s1
	v_ashrrev_i32_e32 v27, 31, v26
	v_lshl_add_u64 v[26:27], v[42:43], 0, v[26:27]
	global_load_dwordx4 v[26:29], v[26:27], off nt
.LBB0_473:
	s_or_b64 exec, exec, s[2:3]
	v_add_u32_e32 v34, 0x600, v1
	v_ashrrev_i32_e32 v34, 9, v34
	v_add_u32_e32 v35, s5, v34
	v_cmp_gt_u32_e32 vcc, 64, v35
	v_mov_b32_e32 v34, 0
	v_mov_b32_e32 v38, 0
	v_mov_b32_e32 v39, 0
	v_mov_b32_e32 v40, 0
	v_mov_b32_e32 v41, 0
	s_and_saveexec_b64 s[2:3], vcc
	s_cbranch_execz .LBB0_475
	v_lshlrev_b32_e32 v35, 6, v35
	v_or3_b32 v35, v35, v82, s4
	s_movk_i32 s1, 0xc00
	v_mul_lo_u32 v36, v35, s1
	v_ashrrev_i32_e32 v37, 31, v36
	v_lshl_add_u64 v[36:37], v[42:43], 0, v[36:37]
	global_load_dwordx4 v[38:41], v[36:37], off nt
.LBB0_475:
	s_or_b64 exec, exec, s[2:3]
	v_add_u32_e32 v44, 0x700, v1
	v_ashrrev_i32_e32 v35, 9, v44
	v_add_u32_e32 v45, s5, v35
	v_cmp_gt_u32_e32 vcc, 64, v45
	v_mov_b32_e32 v35, 0
	v_mov_b32_e32 v36, 0
	v_mov_b32_e32 v37, 0
	s_and_saveexec_b64 s[2:3], vcc
	s_cbranch_execz .LBB0_477
	v_bfe_u32 v34, v44, 3, 6
	v_lshlrev_b32_e32 v35, 6, v45
	v_or3_b32 v34, v35, v34, s4
	s_movk_i32 s1, 0xc00
	v_mul_lo_u32 v34, v34, s1
	v_ashrrev_i32_e32 v35, 31, v34
	v_lshl_add_u64 v[34:35], v[42:43], 0, v[34:35]
	global_load_dwordx4 v[34:37], v[34:35], off nt

.LBB0_535:
	s_and_b64 vcc, exec, s[0:1]
	s_cbranch_vccz .LBB0_539
	s_add_i32 s88, s88, 0xf800
	s_sext_i32_i16 s0, s88
	s_mulk_i32 s0, 0x7879
	s_lshr_b32 s1, s0, 31
	s_ashr_i32 s0, s0, 19
	s_add_i32 s2, s0, s1
	v_mov_b32_e32 v1, v0
	s_mul_i32 s0, s2, 17
	s_sub_i32 s3, s88, s0
	s_waitcnt vmcnt(0)
	v_and_b32_e32 v2, 0xffffffcf, v1
	v_and_b32_e32 v85, 15, v1
	v_ashrrev_i32_e32 v3, 31, v2
	s_sext_i32_i16 s4, s3
	v_lshlrev_b64 v[4:5], 9, v[2:3]
	v_lshlrev_b32_e32 v3, 4, v85
	v_lshl_or_b32 v8, s4, 10, v3
	v_or_b32_e32 v10, 0x300, v8
	v_ashrrev_i32_e32 v11, 31, v10
	v_lshlrev_b64 v[10:11], 5, v[10:11]
	s_sext_i32_i16 s5, s2
	v_mov_b32_e32 v3, 0x88000
	s_bfe_i64 s[0:1], s[2:3], 0x100000
	v_mad_i64_i32 v[10:11], s[2:3], s5, v3, v[10:11]
	v_and_b32_e32 v12, 48, v1
	v_or_b32_e32 v10, v10, v12
	v_lshl_add_u64 v[66:67], s[86:87], 0, v[10:11]
	v_or_b32_e32 v10, 0x200, v8
	v_ashrrev_i32_e32 v11, 31, v10
	v_lshlrev_b64 v[10:11], 5, v[10:11]
	v_mad_i64_i32 v[10:11], s[2:3], s5, v3, v[10:11]
	s_lshl_b64 s[6:7], s[0:1], 17
	v_or_b32_e32 v10, v10, v12
	v_lshl_add_u64 v[68:69], s[86:87], 0, v[10:11]
	v_or_b32_e32 v10, 0x100, v8
	v_lshl_add_u64 v[4:5], s[6:7], 0, v[4:5]
	v_ashrrev_i32_e32 v11, 31, v10
	v_ashrrev_i32_e32 v9, 31, v8
	v_or_b32_e32 v4, v4, v12
	v_lshlrev_b64 v[10:11], 5, v[10:11]
	v_lshlrev_b64 v[8:9], 5, v[8:9]
	v_lshl_add_u64 v[74:75], s[86:87], 0, v[4:5]
	v_or_b32_e32 v4, 16, v2
	v_or_b32_e32 v2, 32, v2
	v_mad_i64_i32 v[10:11], s[2:3], s5, v3, v[10:11]
	v_mad_i64_i32 v[8:9], s[2:3], s5, v3, v[8:9]
	v_ashrrev_i32_e32 v3, 31, v2
	v_or_b32_e32 v6, 48, v1
	v_lshlrev_b64 v[2:3], 9, v[2:3]
	v_ashrrev_i32_e32 v7, 31, v6
	v_lshl_add_u64 v[2:3], s[6:7], 0, v[2:3]
	v_lshlrev_b64 v[6:7], 9, v[6:7]
	v_ashrrev_i32_e32 v5, 31, v4
	v_or_b32_e32 v2, v2, v12
	v_lshlrev_b64 v[4:5], 9, v[4:5]
	v_lshl_add_u64 v[78:79], s[86:87], 0, v[2:3]
	v_lshl_add_u64 v[2:3], s[6:7], 0, v[6:7]
	v_lshl_add_u64 v[4:5], s[6:7], 0, v[4:5]
	v_or_b32_e32 v2, v2, v12
	v_or_b32_e32 v10, v10, v12
	v_or_b32_e32 v8, v8, v12
	v_or_b32_e32 v4, v4, v12
	v_lshl_add_u64 v[80:81], s[86:87], 0, v[2:3]
	v_mov_b32_e32 v2, 0
	v_lshrrev_b32_e32 v84, 4, v1
	v_lshl_add_u64 v[70:71], s[86:87], 0, v[10:11]
	v_lshl_add_u64 v[72:73], s[86:87], 0, v[8:9]
	v_lshl_add_u64 v[76:77], s[86:87], 0, v[4:5]
	s_mul_i32 s64, s5, 0x88000
	s_lshl_b32 s65, s4, 15
	s_add_u32 s64, s64, s65
	s_add_u32 s62, s86, s64
	s_addc_u32 s63, s87, 0
	s_add_u32 s62, s62, 0x2bf1100
	s_addc_u32 s63, s63, 0
	v_lshlrev_b32_e32 v230, 4, v1
	v_lshrrev_b32_e32 v229, 5, v1
	v_mul_u32_u24_e32 v229, 0x210, v229
	v_and_b32_e32 v231, 31, v1
	v_lshl_add_u32 v229, v231, 4, v229
	v_and_b32_e32 v228, 15, v1
	v_mul_u32_u24_e32 v228, 0x210, v228
	v_bfe_u32 v231, v1, 4, 2
	v_lshl_add_u32 v228, v231, 4, v228
	global_load_dwordx4 v[14:17], v230, s[62:63] nt
	v_add_u32_e32 v230, 0x1000, v230
	global_load_dwordx4 v[18:21], v230, s[62:63] nt
	v_add_u32_e32 v230, 0x1000, v230
	global_load_dwordx4 v[22:25], v230, s[62:63] nt
	v_add_u32_e32 v230, 0x1000, v230
	global_load_dwordx4 v[26:29], v230, s[62:63] nt
	v_add_u32_e32 v230, 0x1000, v230
	global_load_dwordx4 v[30:33], v230, s[62:63] nt
	v_add_u32_e32 v230, 0x1000, v230
	global_load_dwordx4 v[34:37], v230, s[62:63] nt
	v_add_u32_e32 v230, 0x1000, v230
	global_load_dwordx4 v[38:41], v230, s[62:63] nt
	v_add_u32_e32 v230, 0x1000, v230
	global_load_dwordx4 v[42:45], v230, s[62:63] nt
	s_waitcnt vmcnt(0)
	ds_write_b128 v229, v[14:17]
	ds_write_b128 v229, v[18:21] offset:4224
	ds_write_b128 v229, v[22:25] offset:8448
	ds_write_b128 v229, v[26:29] offset:12672
	ds_write_b128 v229, v[30:33] offset:16896
	ds_write_b128 v229, v[34:37] offset:21120
	ds_write_b128 v229, v[38:41] offset:25344
	ds_write_b128 v229, v[42:45] offset:29568
	s_waitcnt lgkmcnt(0)
	s_barrier
	s_mov_b64 s[2:3], 0
	v_mov_b32_e32 v3, v2
	v_mov_b32_e32 v4, v2
	v_mov_b32_e32 v5, v2
	v_mov_b32_e32 v6, v2
	v_mov_b32_e32 v7, v2
	v_mov_b32_e32 v8, v2
	v_mov_b32_e32 v9, v2
	v_mov_b32_e32 v10, v2
	v_mov_b32_e32 v11, v2
	v_mov_b32_e32 v12, v2
	v_mov_b32_e32 v13, v2
	v_mov_b32_e32 v38, v2
	v_mov_b32_e32 v39, v2
	v_mov_b32_e32 v40, v2
	v_mov_b32_e32 v41, v2
	v_mov_b32_e32 v50, v2
	v_mov_b32_e32 v51, v2
	v_mov_b32_e32 v52, v2
	v_mov_b32_e32 v53, v2
	v_mov_b32_e32 v54, v2
	v_mov_b32_e32 v55, v2
	v_mov_b32_e32 v56, v2
	v_mov_b32_e32 v57, v2
	v_mov_b32_e32 v58, v2
	v_mov_b32_e32 v59, v2
	v_mov_b32_e32 v60, v2
	v_mov_b32_e32 v61, v2
	v_mov_b32_e32 v62, v2
	v_mov_b32_e32 v63, v2
	v_mov_b32_e32 v64, v2
	v_mov_b32_e32 v65, v2
	v_mov_b32_e32 v46, v2
	v_mov_b32_e32 v47, v2
	v_mov_b32_e32 v48, v2
	v_mov_b32_e32 v49, v2
	v_mov_b32_e32 v42, v2
	v_mov_b32_e32 v43, v2
	v_mov_b32_e32 v44, v2
	v_mov_b32_e32 v45, v2
	v_mov_b32_e32 v34, v2
	v_mov_b32_e32 v35, v2
	v_mov_b32_e32 v36, v2
	v_mov_b32_e32 v37, v2
	v_mov_b32_e32 v26, v2
	v_mov_b32_e32 v27, v2
	v_mov_b32_e32 v28, v2
	v_mov_b32_e32 v29, v2
	v_mov_b32_e32 v30, v2
	v_mov_b32_e32 v31, v2
	v_mov_b32_e32 v32, v2
	v_mov_b32_e32 v33, v2
	v_mov_b32_e32 v22, v2
	v_mov_b32_e32 v23, v2
	v_mov_b32_e32 v24, v2
	v_mov_b32_e32 v25, v2
	v_mov_b32_e32 v18, v2
	v_mov_b32_e32 v19, v2
	v_mov_b32_e32 v20, v2
	v_mov_b32_e32 v21, v2
	v_mov_b32_e32 v14, v2
	v_mov_b32_e32 v15, v2
	v_mov_b32_e32 v16, v2
	v_mov_b32_e32 v17, v2
	s_mov_b32 s5, 0x9771000
	s_mov_b32 s6, 0x2bf1000

.LBB0_592:
	s_add_i32 s4, s1, s0
	s_cmpk_gt_i32 s4, 0x4bf
	s_cbranch_scc0 .LBB0_630
	s_cmpk_gt_u32 s4, 0x6bf
	s_cbranch_scc0 .LBB0_631
	v_mov_b32_e32 v16, v0
	s_movk_i32 s4, 0x100
	v_ashrrev_i32_e32 v17, 31, v16
	s_and_b32 s20, s7, 0x1f0
	v_cmp_gt_i32_e64 s[4:5], s4, v16
	v_lshl_add_u64 v[18:19], v[16:17], 2, s[90:91]
	s_waitcnt vmcnt(0)
	v_mov_b32_e32 v3, 0
	v_mov_b32_e32 v2, 0
	s_and_saveexec_b64 s[14:15], s[4:5]
	s_cbranch_execz .LBB0_596
	s_lshl_b32 s88, s20, 11
	v_lshl_add_u64 v[4:5], v[18:19], 0, s[88:89]
	global_load_dword v2, v[4:5], off nt
.LBB0_596:
	s_or_b64 exec, exec, s[14:15]
	s_and_saveexec_b64 s[14:15], s[4:5]
	s_cbranch_execz .LBB0_598
	s_lshl_b32 s88, s20, 11
	v_lshl_add_u64 v[4:5], v[18:19], 0, s[88:89]
	global_load_dword v3, v[4:5], off offset:2048 nt
.LBB0_598:
	s_or_b64 exec, exec, s[14:15]
	v_mov_b32_e32 v5, 0
	v_mov_b32_e32 v4, 0
	s_and_saveexec_b64 s[14:15], s[4:5]
	s_cbranch_execz .LBB0_600
	s_lshl_b32 s88, s20, 11
	v_lshl_add_u64 v[6:7], v[18:19], 0, s[88:89]
	v_add_co_u32_e32 v6, vcc, 0x1000, v6
	s_nop 1
	v_addc_co_u32_e32 v7, vcc, 0, v7, vcc
	global_load_dword v4, v[6:7], off nt
.LBB0_600:
	s_or_b64 exec, exec, s[14:15]
	s_and_saveexec_b64 s[14:15], s[4:5]
	s_cbranch_execz .LBB0_602
	s_lshl_b32 s88, s20, 11
	v_lshl_add_u64 v[6:7], v[18:19], 0, s[88:89]
	v_add_co_u32_e32 v6, vcc, 0x1000, v6
	s_nop 1
	v_addc_co_u32_e32 v7, vcc, 0, v7, vcc
	global_load_dword v5, v[6:7], off offset:2048 nt
.LBB0_602:
	s_or_b64 exec, exec, s[14:15]
	v_mov_b32_e32 v7, 0
	v_mov_b32_e32 v6, 0
	s_and_saveexec_b64 s[14:15], s[4:5]
	s_cbranch_execz .LBB0_604
	s_lshl_b32 s88, s20, 11
	v_lshl_add_u64 v[8:9], v[18:19], 0, s[88:89]
	v_add_co_u32_e32 v8, vcc, 0x2000, v8
	s_nop 1
	v_addc_co_u32_e32 v9, vcc, 0, v9, vcc
	global_load_dword v6, v[8:9], off nt
.LBB0_604:
	s_or_b64 exec, exec, s[14:15]
	s_and_saveexec_b64 s[14:15], s[4:5]
	s_cbranch_execz .LBB0_606
	s_lshl_b32 s88, s20, 11
	v_lshl_add_u64 v[8:9], v[18:19], 0, s[88:89]
	v_add_co_u32_e32 v8, vcc, 0x2000, v8
	s_nop 1
	v_addc_co_u32_e32 v9, vcc, 0, v9, vcc
	global_load_dword v7, v[8:9], off offset:2048 nt
.LBB0_606:
	s_or_b64 exec, exec, s[14:15]
	v_mov_b32_e32 v9, 0
	v_mov_b32_e32 v8, 0
	s_and_saveexec_b64 s[14:15], s[4:5]
	s_cbranch_execz .LBB0_608
	s_lshl_b32 s88, s20, 11
	v_lshl_add_u64 v[10:11], v[18:19], 0, s[88:89]
	v_add_co_u32_e32 v10, vcc, 0x3000, v10
	s_nop 1
	v_addc_co_u32_e32 v11, vcc, 0, v11, vcc
	global_load_dword v8, v[10:11], off nt
.LBB0_608:
	s_or_b64 exec, exec, s[14:15]
	s_and_saveexec_b64 s[14:15], s[4:5]
	s_cbranch_execz .LBB0_610
	s_lshl_b32 s88, s20, 11
	v_lshl_add_u64 v[10:11], v[18:19], 0, s[88:89]
	v_add_co_u32_e32 v10, vcc, 0x3000, v10
	s_nop 1
	v_addc_co_u32_e32 v11, vcc, 0, v11, vcc
	global_load_dword v9, v[10:11], off offset:2048 nt
.LBB0_610:
	s_or_b64 exec, exec, s[14:15]
	v_mov_b32_e32 v11, 0
	v_mov_b32_e32 v10, 0
	s_and_saveexec_b64 s[14:15], s[4:5]
	s_cbranch_execz .LBB0_612
	s_lshl_b32 s88, s20, 11
	v_lshl_add_u64 v[12:13], v[18:19], 0, s[88:89]
	v_add_co_u32_e32 v12, vcc, 0x4000, v12
	s_nop 1
	v_addc_co_u32_e32 v13, vcc, 0, v13, vcc
	global_load_dword v10, v[12:13], off nt
.LBB0_612:
	s_or_b64 exec, exec, s[14:15]
	s_and_saveexec_b64 s[14:15], s[4:5]
	s_cbranch_execz .LBB0_614
	s_lshl_b32 s88, s20, 11
	v_lshl_add_u64 v[12:13], v[18:19], 0, s[88:89]
	v_add_co_u32_e32 v12, vcc, 0x4000, v12
	s_nop 1
	v_addc_co_u32_e32 v13, vcc, 0, v13, vcc
	global_load_dword v11, v[12:13], off offset:2048 nt
.LBB0_614:
	s_or_b64 exec, exec, s[14:15]
	v_mov_b32_e32 v13, 0
	v_mov_b32_e32 v12, 0
	s_and_saveexec_b64 s[14:15], s[4:5]
	s_cbranch_execz .LBB0_616
	s_lshl_b32 s88, s20, 11
	v_lshl_add_u64 v[14:15], v[18:19], 0, s[88:89]
	v_add_co_u32_e32 v14, vcc, 0x5000, v14
	s_nop 1
	v_addc_co_u32_e32 v15, vcc, 0, v15, vcc
	global_load_dword v12, v[14:15], off nt
.LBB0_616:
	s_or_b64 exec, exec, s[14:15]
	s_and_saveexec_b64 s[14:15], s[4:5]
	s_cbranch_execz .LBB0_618
	s_lshl_b32 s88, s20, 11
	v_lshl_add_u64 v[14:15], v[18:19], 0, s[88:89]
	v_add_co_u32_e32 v14, vcc, 0x5000, v14
	s_nop 1
	v_addc_co_u32_e32 v15, vcc, 0, v15, vcc
	global_load_dword v13, v[14:15], off offset:2048 nt
.LBB0_618:
	s_or_b64 exec, exec, s[14:15]
	v_mov_b32_e32 v15, 0
	v_mov_b32_e32 v14, 0
	s_and_saveexec_b64 s[14:15], s[4:5]
	s_cbranch_execz .LBB0_620
	s_lshl_b32 s88, s20, 11
	v_lshl_add_u64 v[20:21], v[18:19], 0, s[88:89]
	v_add_co_u32_e32 v20, vcc, 0x6000, v20
	s_nop 1
	v_addc_co_u32_e32 v21, vcc, 0, v21, vcc
	global_load_dword v14, v[20:21], off nt
.LBB0_620:
	s_or_b64 exec, exec, s[14:15]
	s_and_saveexec_b64 s[14:15], s[4:5]
	s_cbranch_execz .LBB0_622
	s_lshl_b32 s88, s20, 11
	v_lshl_add_u64 v[20:21], v[18:19], 0, s[88:89]
	v_add_co_u32_e32 v20, vcc, 0x6000, v20
	s_nop 1
	v_addc_co_u32_e32 v21, vcc, 0, v21, vcc
	global_load_dword v15, v[20:21], off offset:2048 nt
.LBB0_622:
	s_or_b64 exec, exec, s[14:15]
	v_mov_b32_e32 v21, 0
	v_mov_b32_e32 v20, 0
	s_and_saveexec_b64 s[14:15], s[4:5]
	s_cbranch_execz .LBB0_624
	s_lshl_b32 s88, s20, 11
	v_lshl_add_u64 v[22:23], v[18:19], 0, s[88:89]
	v_add_co_u32_e32 v22, vcc, 0x7000, v22
	s_nop 1
	v_addc_co_u32_e32 v23, vcc, 0, v23, vcc
	global_load_dword v20, v[22:23], off nt
.LBB0_624:
	s_or_b64 exec, exec, s[14:15]
	s_and_saveexec_b64 s[14:15], s[4:5]
	s_cbranch_execz .LBB0_626
	s_lshl_b32 s88, s20, 11
	v_lshl_add_u64 v[18:19], v[18:19], 0, s[88:89]
	v_add_co_u32_e32 v18, vcc, 0x7000, v18
	s_nop 1
	v_addc_co_u32_e32 v19, vcc, 0, v19, vcc
	global_load_dword v21, v[18:19], off offset:2048 nt

.LBB0_632:
	s_and_b32 s88, s29, 0x7fffff00
	s_add_i32 s4, s7, 0xffffb400
	s_and_b32 s20, s4, 0x7f0
	s_lshl_b64 s[18:19], s[88:89], 2
	v_mov_b32_e32 v16, v0
	s_add_u32 s18, s8, s18
	s_movk_i32 s4, 0x100
	v_ashrrev_i32_e32 v17, 31, v16
	s_addc_u32 s19, s9, s19
	v_cmp_gt_i32_e64 s[4:5], s4, v16
	v_lshl_add_u64 v[18:19], v[16:17], 2, s[18:19]
	s_waitcnt vmcnt(0)
	v_mov_b32_e32 v82, 1.0
	v_mov_b32_e32 v83, 1.0
	v_mov_b32_e32 v84, 1.0
	v_mov_b32_e32 v85, 1.0
	v_mov_b32_e32 v86, 1.0
	v_mov_b32_e32 v87, 1.0
	v_mov_b32_e32 v88, 1.0
	v_mov_b32_e32 v89, 1.0
	v_mov_b32_e32 v90, 1.0
	v_mov_b32_e32 v91, 1.0
	v_mov_b32_e32 v92, 1.0
	v_mov_b32_e32 v93, 1.0
	v_mov_b32_e32 v94, 1.0
	v_mov_b32_e32 v95, 1.0
	v_mov_b32_e32 v96, 1.0
	v_mov_b32_e32 v97, 1.0
	v_mov_b32_e32 v2, 0
	s_and_saveexec_b64 s[18:19], s[4:5]
	s_cbranch_execz .LBB0_634
	s_lshl_b32 vcc_lo, s20, 12
	s_mov_b32 vcc_hi, s89
	v_lshl_add_u64 v[2:3], v[18:19], 0, vcc
	global_load_dword v2, v[2:3], off nt

.LBB0_636:
	v_mov_b32_e32 v3, 0
	s_and_saveexec_b64 s[18:19], s[4:5]
	s_cbranch_execz .LBB0_638
	s_lshl_b32 vcc_lo, s20, 12
	s_mov_b32 vcc_hi, s89
	v_lshl_add_u64 v[4:5], v[18:19], 0, vcc
	v_add_co_u32_e32 v4, vcc, 0x1000, v4
	s_nop 1
	v_addc_co_u32_e32 v5, vcc, 0, v5, vcc
	global_load_dword v3, v[4:5], off nt

.LBB0_640:
	v_mov_b32_e32 v4, 0
	s_and_saveexec_b64 s[18:19], s[4:5]
	s_cbranch_execz .LBB0_642
	s_lshl_b32 vcc_lo, s20, 12
	s_mov_b32 vcc_hi, s89
	v_lshl_add_u64 v[4:5], v[18:19], 0, vcc
	v_add_co_u32_e32 v4, vcc, 0x2000, v4
	s_nop 1
	v_addc_co_u32_e32 v5, vcc, 0, v5, vcc
	global_load_dword v4, v[4:5], off nt

.LBB0_644:
	v_mov_b32_e32 v5, 0
	s_and_saveexec_b64 s[18:19], s[4:5]
	s_cbranch_execz .LBB0_646
	s_lshl_b32 vcc_lo, s20, 12
	s_mov_b32 vcc_hi, s89
	v_lshl_add_u64 v[6:7], v[18:19], 0, vcc
	v_add_co_u32_e32 v6, vcc, 0x3000, v6
	s_nop 1
	v_addc_co_u32_e32 v7, vcc, 0, v7, vcc
	global_load_dword v5, v[6:7], off nt

.LBB0_648:
	v_mov_b32_e32 v6, 0
	s_and_saveexec_b64 s[18:19], s[4:5]
	s_cbranch_execz .LBB0_650
	s_lshl_b32 vcc_lo, s20, 12
	s_mov_b32 vcc_hi, s89
	v_lshl_add_u64 v[6:7], v[18:19], 0, vcc
	v_add_co_u32_e32 v6, vcc, 0x4000, v6
	s_nop 1
	v_addc_co_u32_e32 v7, vcc, 0, v7, vcc
	global_load_dword v6, v[6:7], off nt

.LBB0_652:
	v_mov_b32_e32 v7, 0
	s_and_saveexec_b64 s[18:19], s[4:5]
	s_cbranch_execz .LBB0_654
	s_lshl_b32 vcc_lo, s20, 12
	s_mov_b32 vcc_hi, s89
	v_lshl_add_u64 v[8:9], v[18:19], 0, vcc
	v_add_co_u32_e32 v8, vcc, 0x5000, v8
	s_nop 1
	v_addc_co_u32_e32 v9, vcc, 0, v9, vcc
	global_load_dword v7, v[8:9], off nt

.LBB0_656:
	v_mov_b32_e32 v8, 0
	s_and_saveexec_b64 s[18:19], s[4:5]
	s_cbranch_execz .LBB0_658
	s_lshl_b32 vcc_lo, s20, 12
	s_mov_b32 vcc_hi, s89
	v_lshl_add_u64 v[8:9], v[18:19], 0, vcc
	v_add_co_u32_e32 v8, vcc, 0x6000, v8
	s_nop 1
	v_addc_co_u32_e32 v9, vcc, 0, v9, vcc
	global_load_dword v8, v[8:9], off nt

.LBB0_660:
	v_mov_b32_e32 v9, 0
	s_and_saveexec_b64 s[18:19], s[4:5]
	s_cbranch_execz .LBB0_662
	s_lshl_b32 vcc_lo, s20, 12
	s_mov_b32 vcc_hi, s89
	v_lshl_add_u64 v[10:11], v[18:19], 0, vcc
	v_add_co_u32_e32 v10, vcc, 0x7000, v10
	s_nop 1
	v_addc_co_u32_e32 v11, vcc, 0, v11, vcc
	global_load_dword v9, v[10:11], off nt

.LBB0_664:
	v_mov_b32_e32 v10, 0
	s_and_saveexec_b64 s[18:19], s[4:5]
	s_cbranch_execz .LBB0_666
	s_lshl_b32 vcc_lo, s20, 12
	s_mov_b32 vcc_hi, s89
	v_lshl_add_u64 v[10:11], v[18:19], 0, vcc
	v_add_co_u32_e32 v10, vcc, 0x8000, v10
	s_nop 1
	v_addc_co_u32_e32 v11, vcc, 0, v11, vcc
	global_load_dword v10, v[10:11], off nt

.LBB0_668:
	v_mov_b32_e32 v11, 0
	s_and_saveexec_b64 s[18:19], s[4:5]
	s_cbranch_execz .LBB0_670
	s_lshl_b32 vcc_lo, s20, 12
	s_mov_b32 vcc_hi, s89
	v_lshl_add_u64 v[12:13], v[18:19], 0, vcc
	v_add_co_u32_e32 v12, vcc, 0x9000, v12
	s_nop 1
	v_addc_co_u32_e32 v13, vcc, 0, v13, vcc
	global_load_dword v11, v[12:13], off nt

.LBB0_672:
	v_mov_b32_e32 v12, 0
	s_and_saveexec_b64 s[18:19], s[4:5]
	s_cbranch_execz .LBB0_674
	s_lshl_b32 vcc_lo, s20, 12
	s_mov_b32 vcc_hi, s89
	v_lshl_add_u64 v[12:13], v[18:19], 0, vcc
	v_add_co_u32_e32 v12, vcc, 0xa000, v12
	s_nop 1
	v_addc_co_u32_e32 v13, vcc, 0, v13, vcc
	global_load_dword v12, v[12:13], off nt

.LBB0_676:
	v_mov_b32_e32 v13, 0
	s_and_saveexec_b64 s[18:19], s[4:5]
	s_cbranch_execz .LBB0_678
	s_lshl_b32 vcc_lo, s20, 12
	s_mov_b32 vcc_hi, s89
	v_lshl_add_u64 v[14:15], v[18:19], 0, vcc
	v_add_co_u32_e32 v14, vcc, 0xb000, v14
	s_nop 1
	v_addc_co_u32_e32 v15, vcc, 0, v15, vcc
	global_load_dword v13, v[14:15], off nt

.LBB0_680:
	v_mov_b32_e32 v14, 0
	s_and_saveexec_b64 s[18:19], s[4:5]
	s_cbranch_execz .LBB0_682
	s_lshl_b32 vcc_lo, s20, 12
	s_mov_b32 vcc_hi, s89
	v_lshl_add_u64 v[14:15], v[18:19], 0, vcc
	v_add_co_u32_e32 v14, vcc, 0xc000, v14
	s_nop 1
	v_addc_co_u32_e32 v15, vcc, 0, v15, vcc
	global_load_dword v14, v[14:15], off nt

.LBB0_684:
	v_mov_b32_e32 v15, 0
	s_and_saveexec_b64 s[18:19], s[4:5]
	s_cbranch_execz .LBB0_686
	s_lshl_b32 vcc_lo, s20, 12
	s_mov_b32 vcc_hi, s89
	v_lshl_add_u64 v[20:21], v[18:19], 0, vcc
	v_add_co_u32_e32 v20, vcc, 0xd000, v20
	s_nop 1
	v_addc_co_u32_e32 v21, vcc, 0, v21, vcc
	global_load_dword v15, v[20:21], off nt

.LBB0_688:
	v_mov_b32_e32 v20, 0
	s_and_saveexec_b64 s[18:19], s[4:5]
	s_cbranch_execz .LBB0_690
	s_lshl_b32 vcc_lo, s20, 12
	s_mov_b32 vcc_hi, s89
	v_lshl_add_u64 v[20:21], v[18:19], 0, vcc
	v_add_co_u32_e32 v20, vcc, 0xe000, v20
	s_nop 1
	v_addc_co_u32_e32 v21, vcc, 0, v21, vcc
	global_load_dword v20, v[20:21], off nt

.LBB0_692:
	v_mov_b32_e32 v21, 0
	s_and_saveexec_b64 s[18:19], s[4:5]
	s_cbranch_execz .LBB0_694
	s_lshl_b32 s4, s20, 12
	s_mov_b32 s5, s89
	v_lshl_add_u64 v[18:19], v[18:19], 0, s[4:5]
	v_add_co_u32_e32 v18, vcc, 0xf000, v18
	s_nop 1
	v_addc_co_u32_e32 v19, vcc, 0, v19, vcc
	global_load_dword v21, v[18:19], off nt

.LBB0_699:
	v_mov_b32_e32 v16, v0
	s_and_b32 s20, s7, 0x3f0
	s_waitcnt vmcnt(0)
	v_mov_b32_e32 v3, 0
	v_ashrrev_i32_e32 v17, 31, v16
	v_cmp_gt_i32_e64 s[4:5], s28, v16
	v_lshl_add_u64 v[18:19], v[16:17], 2, s[16:17]
	s_mul_i32 s88, s20, 0x4880
	v_mov_b32_e32 v2, 0
	s_and_saveexec_b64 s[18:19], s[4:5]
	s_cbranch_execz .LBB0_701
	v_lshl_add_u64 v[4:5], v[18:19], 0, s[88:89]
	global_load_dword v2, v[4:5], off nt
.LBB0_701:
	s_or_b64 exec, exec, s[18:19]
	s_and_saveexec_b64 s[18:19], s[4:5]
	s_cbranch_execz .LBB0_703
	v_lshl_add_u64 v[4:5], v[18:19], 0, s[88:89]
	v_add_co_u32_e32 v4, vcc, 0x4000, v4
	s_nop 1
	v_addc_co_u32_e32 v5, vcc, 0, v5, vcc
	global_load_dword v3, v[4:5], off offset:2176 nt
.LBB0_703:
	s_or_b64 exec, exec, s[18:19]
	v_mov_b32_e32 v5, 0
	v_mov_b32_e32 v4, 0
	s_and_saveexec_b64 s[18:19], s[4:5]
	s_cbranch_execz .LBB0_705
	v_lshl_add_u64 v[6:7], v[18:19], 0, s[88:89]
	v_add_co_u32_e32 v6, vcc, 0x9000, v6
	s_nop 1
	v_addc_co_u32_e32 v7, vcc, 0, v7, vcc
	global_load_dword v4, v[6:7], off offset:256 nt
.LBB0_705:
	s_or_b64 exec, exec, s[18:19]
	s_and_saveexec_b64 s[18:19], s[4:5]
	s_cbranch_execz .LBB0_707
	v_lshl_add_u64 v[6:7], v[18:19], 0, s[88:89]
	v_add_co_u32_e32 v6, vcc, 0xd000, v6
	s_nop 1
	v_addc_co_u32_e32 v7, vcc, 0, v7, vcc
	global_load_dword v5, v[6:7], off offset:2432 nt
.LBB0_707:
	s_or_b64 exec, exec, s[18:19]
	v_mov_b32_e32 v7, 0
	v_mov_b32_e32 v6, 0
	s_and_saveexec_b64 s[18:19], s[4:5]
	s_cbranch_execz .LBB0_709
	v_lshl_add_u64 v[8:9], v[18:19], 0, s[88:89]
	v_add_co_u32_e32 v8, vcc, 0x12000, v8
	s_nop 1
	v_addc_co_u32_e32 v9, vcc, 0, v9, vcc
	global_load_dword v6, v[8:9], off offset:512 nt
.LBB0_709:
	s_or_b64 exec, exec, s[18:19]
	s_and_saveexec_b64 s[18:19], s[4:5]
	s_cbranch_execz .LBB0_711
	v_lshl_add_u64 v[8:9], v[18:19], 0, s[88:89]
	v_add_co_u32_e32 v8, vcc, 0x16000, v8
	s_nop 1
	v_addc_co_u32_e32 v9, vcc, 0, v9, vcc
	global_load_dword v7, v[8:9], off offset:2688 nt
.LBB0_711:
	s_or_b64 exec, exec, s[18:19]
	v_mov_b32_e32 v9, 0
	v_mov_b32_e32 v8, 0
	s_and_saveexec_b64 s[18:19], s[4:5]
	s_cbranch_execz .LBB0_713
	v_lshl_add_u64 v[10:11], v[18:19], 0, s[88:89]
	v_add_co_u32_e32 v10, vcc, 0x1b000, v10
	s_nop 1
	v_addc_co_u32_e32 v11, vcc, 0, v11, vcc
	global_load_dword v8, v[10:11], off offset:768 nt
.LBB0_713:
	s_or_b64 exec, exec, s[18:19]
	s_and_saveexec_b64 s[18:19], s[4:5]
	s_cbranch_execz .LBB0_715
	v_lshl_add_u64 v[10:11], v[18:19], 0, s[88:89]
	v_add_co_u32_e32 v10, vcc, 0x1f000, v10
	s_nop 1
	v_addc_co_u32_e32 v11, vcc, 0, v11, vcc
	global_load_dword v9, v[10:11], off offset:2944 nt
.LBB0_715:
	s_or_b64 exec, exec, s[18:19]
	v_mov_b32_e32 v11, 0
	v_mov_b32_e32 v10, 0
	s_and_saveexec_b64 s[18:19], s[4:5]
	s_cbranch_execz .LBB0_717
	v_lshl_add_u64 v[12:13], v[18:19], 0, s[88:89]
	v_add_co_u32_e32 v12, vcc, 0x24000, v12
	s_nop 1
	v_addc_co_u32_e32 v13, vcc, 0, v13, vcc
	global_load_dword v10, v[12:13], off offset:1024 nt
.LBB0_717:
	s_or_b64 exec, exec, s[18:19]
	s_and_saveexec_b64 s[18:19], s[4:5]
	s_cbranch_execz .LBB0_719
	v_lshl_add_u64 v[12:13], v[18:19], 0, s[88:89]
	v_add_co_u32_e32 v12, vcc, 0x28000, v12
	s_nop 1
	v_addc_co_u32_e32 v13, vcc, 0, v13, vcc
	global_load_dword v11, v[12:13], off offset:3200 nt
.LBB0_719:
	s_or_b64 exec, exec, s[18:19]
	v_mov_b32_e32 v13, 0
	v_mov_b32_e32 v12, 0
	s_and_saveexec_b64 s[18:19], s[4:5]
	s_cbranch_execz .LBB0_721
	v_lshl_add_u64 v[14:15], v[18:19], 0, s[88:89]
	v_add_co_u32_e32 v14, vcc, 0x2d000, v14
	s_nop 1
	v_addc_co_u32_e32 v15, vcc, 0, v15, vcc
	global_load_dword v12, v[14:15], off offset:1280 nt
.LBB0_721:
	s_or_b64 exec, exec, s[18:19]
	s_and_saveexec_b64 s[18:19], s[4:5]
	s_cbranch_execz .LBB0_723
	v_lshl_add_u64 v[14:15], v[18:19], 0, s[88:89]
	v_add_co_u32_e32 v14, vcc, 0x31000, v14
	s_nop 1
	v_addc_co_u32_e32 v15, vcc, 0, v15, vcc
	global_load_dword v13, v[14:15], off offset:3456 nt
.LBB0_723:
	s_or_b64 exec, exec, s[18:19]
	v_mov_b32_e32 v15, 0
	v_mov_b32_e32 v14, 0
	s_and_saveexec_b64 s[18:19], s[4:5]
	s_cbranch_execz .LBB0_725
	v_lshl_add_u64 v[20:21], v[18:19], 0, s[88:89]
	v_add_co_u32_e32 v20, vcc, 0x36000, v20
	s_nop 1
	v_addc_co_u32_e32 v21, vcc, 0, v21, vcc
	global_load_dword v14, v[20:21], off offset:1536 nt
.LBB0_725:
	s_or_b64 exec, exec, s[18:19]
	s_and_saveexec_b64 s[18:19], s[4:5]
	s_cbranch_execz .LBB0_727
	v_lshl_add_u64 v[20:21], v[18:19], 0, s[88:89]
	v_add_co_u32_e32 v20, vcc, 0x3a000, v20
	s_nop 1
	v_addc_co_u32_e32 v21, vcc, 0, v21, vcc
	global_load_dword v15, v[20:21], off offset:3712 nt
.LBB0_727:
	s_or_b64 exec, exec, s[18:19]
	v_mov_b32_e32 v21, 0
	v_mov_b32_e32 v20, 0
	s_and_saveexec_b64 s[18:19], s[4:5]
	s_cbranch_execz .LBB0_729
	v_lshl_add_u64 v[22:23], v[18:19], 0, s[88:89]
	v_add_co_u32_e32 v22, vcc, 0x3f000, v22
	s_nop 1
	v_addc_co_u32_e32 v23, vcc, 0, v23, vcc
	global_load_dword v20, v[22:23], off offset:1792 nt
.LBB0_729:
	s_or_b64 exec, exec, s[18:19]
	s_and_saveexec_b64 s[18:19], s[4:5]
	s_cbranch_execz .LBB0_731
	v_lshl_add_u64 v[18:19], v[18:19], 0, s[88:89]
	v_add_co_u32_e32 v18, vcc, 0x43000, v18
	s_nop 1
	v_addc_co_u32_e32 v19, vcc, 0, v19, vcc
	global_load_dword v21, v[18:19], off offset:3968 nt

.LBB0_1063:
	v_lshl_add_u64 v[64:65], v[18:19], 0, s[0:1]
	global_load_dword v72, v[64:65], off nt
	s_movk_i32 s10, 0x6000
	v_add_co_u32_e32 v73, vcc, s7, v64
	s_nop 1
	v_addc_co_u32_e32 v74, vcc, 0, v65, vcc
	v_mov_b32_e32 v82, v73
	v_mov_b32_e32 v83, v74
	global_load_dword v75, v[82:83], off nt
	v_add_co_u32_e32 v73, vcc, s10, v64
	s_nop 1
	v_addc_co_u32_e32 v74, vcc, 0, v65, vcc
	v_mov_b32_e32 v82, v73
	v_mov_b32_e32 v83, v74
	global_load_dword v76, v[82:83], off nt
	s_mov_b32 s10, 0x9000
	v_add_co_u32_e32 v73, vcc, s10, v64
	s_nop 1
	v_addc_co_u32_e32 v74, vcc, 0, v65, vcc
	v_mov_b32_e32 v82, v73
	v_mov_b32_e32 v83, v74
	global_load_dword v78, v[82:83], off nt
	s_mov_b32 s10, 0xf000
	v_add_co_u32_e32 v73, vcc, s6, v64
	s_nop 1
	v_addc_co_u32_e32 v74, vcc, 0, v65, vcc
	v_mov_b32_e32 v82, v73
	v_mov_b32_e32 v83, v74
	global_load_dword v84, v[82:83], off nt
	v_add_co_u32_e32 v73, vcc, s10, v64
	s_mov_b32 s10, 0x12000
	s_nop 0
	v_addc_co_u32_e32 v74, vcc, 0, v65, vcc
	v_add_co_u32_e32 v82, vcc, s10, v64
	v_mov_b32_e32 v86, v73
	v_mov_b32_e32 v87, v74
	global_load_dword v83, v[86:87], off nt
	v_addc_co_u32_e32 v73, vcc, 0, v65, vcc
	v_mov_b32_e32 v86, v82
	v_mov_b32_e32 v87, v73
	global_load_dword v74, v[86:87], off nt
	s_mov_b32 s10, 0x15000
	v_add_co_u32_e32 v73, vcc, s10, v64
	s_nop 1
	v_addc_co_u32_e32 v82, vcc, 0, v65, vcc
	v_mov_b32_e32 v86, v73
	v_mov_b32_e32 v87, v82
	global_load_dword v85, v[86:87], off nt
	s_mov_b32 s10, 0x1b000
	v_add_co_u32_e32 v73, vcc, s5, v64
	s_nop 1
	v_addc_co_u32_e32 v82, vcc, 0, v65, vcc
	v_mov_b32_e32 v86, v73
	v_mov_b32_e32 v87, v82
	global_load_dword v88, v[86:87], off nt
	v_add_co_u32_e32 v73, vcc, s10, v64
	s_mov_b32 s10, 0x1e000
	s_nop 0
	v_addc_co_u32_e32 v82, vcc, 0, v65, vcc
	v_add_co_u32_e32 v86, vcc, s10, v64
	v_mov_b32_e32 v90, v73
	v_mov_b32_e32 v91, v82
	global_load_dword v87, v[90:91], off nt
	v_addc_co_u32_e32 v73, vcc, 0, v65, vcc
	v_mov_b32_e32 v90, v86
	v_mov_b32_e32 v91, v73
	global_load_dword v82, v[90:91], off nt
	s_mov_b32 s10, 0x21000
	v_add_co_u32_e32 v73, vcc, s10, v64
	s_nop 1
	v_addc_co_u32_e32 v86, vcc, 0, v65, vcc
	v_mov_b32_e32 v90, v73
	v_mov_b32_e32 v91, v86
	global_load_dword v89, v[90:91], off nt
	s_mov_b32 s10, 0x24000
	v_add_co_u32_e32 v73, vcc, s10, v64
	s_nop 1
	v_addc_co_u32_e32 v86, vcc, 0, v65, vcc
	v_mov_b32_e32 v90, v73
	v_mov_b32_e32 v91, v86
	global_load_dword v92, v[90:91], off nt
	s_mov_b32 s10, 0x27000
	v_add_co_u32_e32 v73, vcc, s10, v64
	s_mov_b32 s10, 0x2a000
	s_nop 0
	v_addc_co_u32_e32 v86, vcc, 0, v65, vcc
	v_add_co_u32_e32 v90, vcc, s10, v64
	v_mov_b32_e32 v94, v73
	v_mov_b32_e32 v95, v86
	global_load_dword v91, v[94:95], off nt
	v_addc_co_u32_e32 v73, vcc, 0, v65, vcc
	v_mov_b32_e32 v94, v90
	v_mov_b32_e32 v95, v73
	global_load_dword v86, v[94:95], off nt
	s_mov_b32 s10, 0x2d000
	v_add_co_u32_e32 v73, vcc, s10, v64
	s_nop 1
	v_addc_co_u32_e32 v90, vcc, 0, v65, vcc
	v_mov_b32_e32 v64, v73
	v_mov_b32_e32 v65, v90
	global_load_dword v93, v[64:65], off nt
	v_lshl_add_u64 v[20:21], v[18:19], 0, s[0:1]
	s_waitcnt vmcnt(0)
	v_mov_b32_e32 v48, v72
	ds_read_b128 v[28:31], v26
	ds_read_b128 v[10:13], v26 offset:16
	ds_read_b128 v[6:9], v26 offset:32
	ds_read_b128 v[2:5], v26 offset:48
	ds_read_b128 v[32:35], v26 offset:4096
	s_waitcnt lgkmcnt(4)
	v_mov_b32_e32 v36, v28
	s_movk_i32 s3, 0x6000
	s_add_u32 s0, s0, 0x30000
	s_addc_u32 s1, s1, 0
	s_waitcnt lgkmcnt(0)
	v_mov_b32_e32 v37, v32
	v_mov_b32_e32 v32, v29
	s_cmp_eq_u32 s0, 0x300000
	v_pk_fma_f32 v[24:25], v[48:49], v[36:37], v[24:25] op_sel_hi:[0,1,1]
	ds_read_b128 v[36:39], v26 offset:8192
	ds_read_b128 v[40:43], v26 offset:12288
	ds_read_b128 v[44:47], v26 offset:16384
	s_waitcnt lgkmcnt(2)
	v_mov_b32_e32 v50, v36
	s_waitcnt lgkmcnt(1)
	v_fmac_f32_e32 v17, v48, v40
	s_waitcnt lgkmcnt(0)
	v_mov_b32_e32 v51, v44
	v_pk_fma_f32 v[22:23], v[48:49], v[50:51], v[22:23] op_sel_hi:[0,1,1]
	v_add_co_u32_e32 v48, vcc, s7, v20
	v_mov_b32_e32 v44, v37
	s_nop 0
	v_addc_co_u32_e32 v49, vcc, 0, v21, vcc
	v_mov_b32_e32 v28, v75
	v_pk_fma_f32 v[24:25], v[28:29], v[32:33], v[24:25] op_sel_hi:[0,1,1]
	v_fmac_f32_e32 v17, v28, v41
	v_pk_fma_f32 v[22:23], v[28:29], v[44:45], v[22:23] op_sel_hi:[0,1,1]
	v_add_co_u32_e32 v28, vcc, s3, v20
	v_mov_b32_e32 v32, v30
	s_nop 0
	v_addc_co_u32_e32 v29, vcc, 0, v21, vcc
	v_mov_b32_e32 v28, v76
	v_mov_b32_e32 v33, v34
	s_mov_b32 s3, 0x9000
	v_mov_b32_e32 v34, v31
	v_pk_fma_f32 v[24:25], v[28:29], v[32:33], v[24:25] op_sel_hi:[0,1,1]
	v_mov_b32_e32 v32, v38
	v_mov_b32_e32 v33, v46
	v_fmac_f32_e32 v17, v28, v42
	v_pk_fma_f32 v[22:23], v[28:29], v[32:33], v[22:23] op_sel_hi:[0,1,1]
	v_add_co_u32_e32 v28, vcc, s3, v20
	v_mov_b32_e32 v46, v39
	s_nop 0
	v_addc_co_u32_e32 v29, vcc, 0, v21, vcc
	v_mov_b32_e32 v28, v78
	s_mov_b32 s3, 0xf000
	v_pk_fma_f32 v[40:41], v[28:29], v[46:47], v[22:23] op_sel_hi:[0,1,1]
	v_add_co_u32_e32 v22, vcc, s6, v20
	v_pk_fma_f32 v[30:31], v[28:29], v[34:35], v[24:25] op_sel_hi:[0,1,1]
	s_nop 0
	v_addc_co_u32_e32 v23, vcc, 0, v21, vcc
	v_mov_b32_e32 v42, v84
	ds_read_b128 v[22:25], v26 offset:4112
	v_fmac_f32_e32 v17, v28, v43
	v_mov_b32_e32 v28, v10
	s_waitcnt lgkmcnt(0)
	v_mov_b32_e32 v29, v22
	v_mov_b32_e32 v22, v11
	v_pk_fma_f32 v[44:45], v[42:43], v[28:29], v[30:31] op_sel_hi:[0,1,1]
	ds_read_b128 v[28:31], v26 offset:8208
	ds_read_b128 v[32:35], v26 offset:12304
	ds_read_b128 v[36:39], v26 offset:16400
	s_waitcnt lgkmcnt(2)
	v_mov_b32_e32 v46, v28
	s_waitcnt lgkmcnt(1)
	v_fmac_f32_e32 v17, v42, v32
	s_waitcnt lgkmcnt(0)
	v_mov_b32_e32 v47, v36
	v_pk_fma_f32 v[40:41], v[42:43], v[46:47], v[40:41] op_sel_hi:[0,1,1]
	v_add_co_u32_e32 v42, vcc, s3, v20
	s_mov_b32 s3, 0x12000
	s_nop 0
	v_addc_co_u32_e32 v43, vcc, 0, v21, vcc
	v_add_co_u32_e32 v28, vcc, s3, v20
	v_mov_b32_e32 v10, v83
	v_mov_b32_e32 v36, v29
	v_addc_co_u32_e32 v29, vcc, 0, v21, vcc
	v_mov_b32_e32 v28, v74
	v_mov_b32_e32 v32, v12
	s_mov_b32 s3, 0x15000
	v_pk_fma_f32 v[22:23], v[10:11], v[22:23], v[44:45] op_sel_hi:[0,1,1]
	v_fmac_f32_e32 v17, v10, v33
	v_mov_b32_e32 v33, v24
	v_pk_fma_f32 v[10:11], v[10:11], v[36:37], v[40:41] op_sel_hi:[0,1,1]
	v_pk_fma_f32 v[22:23], v[28:29], v[32:33], v[22:23] op_sel_hi:[0,1,1]
	v_mov_b32_e32 v32, v30
	v_mov_b32_e32 v33, v38
	v_fmac_f32_e32 v17, v28, v34
	v_pk_fma_f32 v[10:11], v[28:29], v[32:33], v[10:11] op_sel_hi:[0,1,1]
	v_add_co_u32_e32 v28, vcc, s3, v20
	v_mov_b32_e32 v38, v31
	s_nop 0
	v_addc_co_u32_e32 v29, vcc, 0, v21, vcc
	v_mov_b32_e32 v12, v85
	v_mov_b32_e32 v24, v13
	s_mov_b32 s3, 0x1b000
	v_pk_fma_f32 v[36:37], v[12:13], v[38:39], v[10:11] op_sel_hi:[0,1,1]
	v_add_co_u32_e32 v10, vcc, s5, v20
	v_pk_fma_f32 v[22:23], v[12:13], v[24:25], v[22:23] op_sel_hi:[0,1,1]
	s_nop 0
	v_addc_co_u32_e32 v11, vcc, 0, v21, vcc
	v_mov_b32_e32 v38, v88
	v_fmac_f32_e32 v17, v12, v35
	ds_read_b128 v[10:13], v26 offset:4128
	v_mov_b32_e32 v24, v6
	s_waitcnt lgkmcnt(0)
	v_mov_b32_e32 v25, v10
	v_mov_b32_e32 v10, v7
	v_pk_fma_f32 v[40:41], v[38:39], v[24:25], v[22:23] op_sel_hi:[0,1,1]
	ds_read_b128 v[22:25], v26 offset:8224
	ds_read_b128 v[28:31], v26 offset:12320
	ds_read_b128 v[32:35], v26 offset:16416
	s_waitcnt lgkmcnt(2)
	v_mov_b32_e32 v42, v22
	s_waitcnt lgkmcnt(1)
	v_fmac_f32_e32 v17, v38, v28
	s_waitcnt lgkmcnt(0)
	v_mov_b32_e32 v43, v32
	v_pk_fma_f32 v[36:37], v[38:39], v[42:43], v[36:37] op_sel_hi:[0,1,1]
	v_add_co_u32_e32 v38, vcc, s3, v20
	s_mov_b32 s3, 0x1e000
	s_nop 0
	v_addc_co_u32_e32 v39, vcc, 0, v21, vcc
	v_add_co_u32_e32 v22, vcc, s3, v20
	v_mov_b32_e32 v6, v87
	v_mov_b32_e32 v32, v23
	v_addc_co_u32_e32 v23, vcc, 0, v21, vcc
	v_mov_b32_e32 v22, v82
	v_mov_b32_e32 v28, v8
	s_mov_b32 s3, 0x21000
	v_pk_fma_f32 v[10:11], v[6:7], v[10:11], v[40:41] op_sel_hi:[0,1,1]
	v_fmac_f32_e32 v17, v6, v29
	v_mov_b32_e32 v29, v12
	v_pk_fma_f32 v[6:7], v[6:7], v[32:33], v[36:37] op_sel_hi:[0,1,1]
	v_pk_fma_f32 v[10:11], v[22:23], v[28:29], v[10:11] op_sel_hi:[0,1,1]
	v_mov_b32_e32 v28, v24
	v_mov_b32_e32 v29, v34
	v_fmac_f32_e32 v17, v22, v30
	v_pk_fma_f32 v[6:7], v[22:23], v[28:29], v[6:7] op_sel_hi:[0,1,1]
	v_add_co_u32_e32 v22, vcc, s3, v20
	v_mov_b32_e32 v34, v25
	s_nop 0
	v_addc_co_u32_e32 v23, vcc, 0, v21, vcc
	v_mov_b32_e32 v8, v89
	s_mov_b32 s3, 0x24000
	v_mov_b32_e32 v12, v9
	v_pk_fma_f32 v[22:23], v[8:9], v[34:35], v[6:7] op_sel_hi:[0,1,1]
	v_add_co_u32_e32 v6, vcc, s3, v20
	v_pk_fma_f32 v[10:11], v[8:9], v[12:13], v[10:11] op_sel_hi:[0,1,1]
	s_nop 0
	v_addc_co_u32_e32 v7, vcc, 0, v21, vcc
	v_mov_b32_e32 v24, v92
	v_fmac_f32_e32 v17, v8, v31
	ds_read_b128 v[6:9], v26 offset:4144
	v_mov_b32_e32 v12, v2
	s_mov_b32 s3, 0x27000
	s_waitcnt lgkmcnt(0)
	v_mov_b32_e32 v13, v6
	v_mov_b32_e32 v6, v3
	v_pk_fma_f32 v[36:37], v[24:25], v[12:13], v[10:11] op_sel_hi:[0,1,1]
	ds_read_b128 v[10:13], v26 offset:8240
	ds_read_b128 v[28:31], v26 offset:12336
	ds_read_b128 v[32:35], v26 offset:16432
	v_add_u32_e32 v26, 64, v26
	s_waitcnt lgkmcnt(2)
	v_mov_b32_e32 v38, v10
	s_waitcnt lgkmcnt(1)
	v_fmac_f32_e32 v17, v24, v28
	s_waitcnt lgkmcnt(0)
	v_mov_b32_e32 v39, v32
	v_pk_fma_f32 v[22:23], v[24:25], v[38:39], v[22:23] op_sel_hi:[0,1,1]
	v_add_co_u32_e32 v24, vcc, s3, v20
	s_mov_b32 s3, 0x2a000
	s_nop 0
	v_addc_co_u32_e32 v25, vcc, 0, v21, vcc
	v_add_co_u32_e32 v10, vcc, s3, v20
	v_mov_b32_e32 v2, v91
	v_mov_b32_e32 v32, v11
	v_addc_co_u32_e32 v11, vcc, 0, v21, vcc
	v_mov_b32_e32 v10, v86
	s_mov_b32 s3, 0x2d000
	v_pk_fma_f32 v[6:7], v[2:3], v[6:7], v[36:37] op_sel_hi:[0,1,1]
	v_fmac_f32_e32 v17, v2, v29
	v_pk_fma_f32 v[2:3], v[2:3], v[32:33], v[22:23] op_sel_hi:[0,1,1]
	v_mov_b32_e32 v22, v4
	v_mov_b32_e32 v23, v8
	v_pk_fma_f32 v[6:7], v[10:11], v[22:23], v[6:7] op_sel_hi:[0,1,1]
	v_mov_b32_e32 v22, v12
	v_mov_b32_e32 v23, v34
	v_fmac_f32_e32 v17, v10, v30
	v_pk_fma_f32 v[2:3], v[10:11], v[22:23], v[2:3] op_sel_hi:[0,1,1]
	v_add_co_u32_e32 v10, vcc, s3, v20
	v_mov_b32_e32 v8, v5
	s_nop 0
	v_addc_co_u32_e32 v11, vcc, 0, v21, vcc
	v_mov_b32_e32 v4, v93
	v_mov_b32_e32 v34, v13
	v_pk_fma_f32 v[24:25], v[4:5], v[8:9], v[6:7] op_sel_hi:[0,1,1]
	v_fmac_f32_e32 v17, v4, v31
	v_pk_fma_f32 v[22:23], v[4:5], v[34:35], v[2:3] op_sel_hi:[0,1,1]
	s_cbranch_scc0 .LBB0_1063
	s_movk_i32 s0, 0x500
	v_mul_lo_u32 v2, v15, s0
	s_movk_i32 s0, 0x140
	v_lshl_or_b32 v2, v1, 2, v2
	v_cmp_gt_i32_e32 vcc, s0, v14
	ds_write2st64_b32 v2, v24, v25 offset0:80 offset1:81
	ds_write2st64_b32 v2, v22, v17 offset0:82 offset1:83
	ds_write_b32 v2, v23 offset:21504
	s_waitcnt lgkmcnt(0)
	s_barrier
	s_and_saveexec_b64 s[0:1], vcc
	s_cbranch_execz .LBB0_1069
	s_mul_i32 s5, s4, 0xc00
	s_and_b32 s2, s2, 48
	s_cmp_eq_u32 s2, 16
	v_add_u32_e32 v4, s5, v16
	s_cselect_b64 s[2:3], -1, 0
	s_mul_i32 s6, s4, 5
	v_lshlrev_b32_e32 v130, 2, v4
	s_lshl_b32 s4, s4, 11
	v_lshl_add_u64 v[2:3], s[46:47], 0, v[130:131]
	v_subrev_u32_e32 v130, s4, v4
	v_readlane_b32 s4, v253, 25
	v_lshl_add_u64 v[4:5], v[130:131], 2, s[48:49]
	v_lshlrev_b32_e32 v130, 2, v16
	v_readlane_b32 s5, v253, 26
	v_mov_b32_e32 v8, 0x5000
	v_lshlrev_b32_e32 v1, 2, v1
	v_lshl_add_u64 v[6:7], s[4:5], 0, v[130:131]
	v_lshl_add_u32 v8, v14, 2, v8
	s_mov_b64 s[4:5], 0
	s_branch .LBB0_1067
